# fat GEMM phases (P1,P3,P9): drop per-unit 128x v_mov accumulator zeroing; first-iteration MFMAs take SrcC=0 (out-of-line variant, branch before the slot barrier)
# speedup vs baseline: 1.0067x; 1.0067x over previous
; template <class Epi>
; __device__ __forceinline__ void gemm_phase(LAS unsigned char* lds, const Gemm g, const Sched& S, const Epi& E) {
;     ...
;         const bool has_next = S.next(ui + 1, nxt);
;         const char* nA = has_next ? (const char*)g.A + (size_t)nxt.pm * tstepA + (size_t)nxt.part * g.koff * 2 : cA; const char* nB = has_next ? (const char*)g.Bt + (size_t)nxt.pn * tstepB + (size_t)nxt.part * g.koff * 2 : cB;
;     ...
;         if (!(Epi::KEEP_PART0 && cur.part == 0))
; #pragma unroll
;         for (int a = 0; a < 2; ++a)
; #pragma unroll
;             for (int b = 0; b < 2; ++b)
; #pragma unroll
;                 for (int m = 0; m < 4; ++m)
; #pragma unroll
;                     for (int n = 0; n < 2; ++n) acc[a][b][m][n] = (f32x4){0.f, 0.f, 0.f, 0.f};
;         cur = nxt; cA = nA; cB = nB; ++ui;
.LBB0_583:
	s_ashr_i32 s21, s20, 31
	s_lshl_b64 s[22:23], s[20:21], 19
	s_add_u32 s22, s88, s22
	s_addc_u32 s23, s89, s23
	s_and_b64 s[28:29], s[0:1], exec
	s_cselect_b32 s21, s23, s35
	s_cselect_b32 s82, s22, s34
	s_ashr_i32 s19, s18, 31
	s_lshl_b64 s[28:29], s[18:19], 19
	s_add_u32 s28, s50, s28
	s_addc_u32 s29, s51, s29
	s_and_b64 s[40:41], s[0:1], exec
	s_cselect_b32 s19, s29, s39
	s_cselect_b32 s83, s28, s38
	s_add_u32 s34, s34, 0x40080
	s_addc_u32 s35, s35, 0
	s_add_u32 s84, s38, 0x100
	s_addc_u32 s85, s39, 0
	s_mov_b32 s86, -2

; #define PG8_STAGE(bufoff, gbase, voff) do { _Pragma("unroll") for (int _i = 0; _i < 2; ++_i) \
;         __builtin_amdgcn_global_load_lds((const unsigned*)((const char*)(gbase) + (voff)[_i]), (LAS unsigned*)(lds + (bufoff) + ldsw + _i * 8192), 16, 0, 0); } while (0)
; #define PG8_LDA(dst, b, h) do { _Pragma("unroll") for (int m = 0; m < 4; ++m) _Pragma("unroll") for (int k = 0; k < 2; ++k) dst[m][k] = *(const LAS bf16x8*)(lds + PG8_SA(b, h) + aoff + m * 2048 + k * 1024); } while (0)
; #define PG8_MMA(ai, bj, At, Bt) do { __builtin_amdgcn_s_setprio(1); _Pragma("unroll") for (int m = 0; m < 4; ++m) _Pragma("unroll") for (int n = 0; n < 2; ++n) _Pragma("unroll") for (int k = 0; k < 2; ++k) \
;         acc[ai][bj][m][n] = __builtin_amdgcn_mfma_f32_16x16x32_bf16(Bt[n][k], At[m][k], acc[ai][bj][m][n], 0, 0, 0); __builtin_amdgcn_s_setprio(0); } while (0)
; #define PG8_WAIT_V(n) asm volatile("s_waitcnt vmcnt(" #n ")" ::: "memory")
; #define PG8_WAIT_L(n) asm volatile("s_waitcnt lgkmcnt(" #n ")" ::: "memory")
; #define PG8_BAR __builtin_amdgcn_s_barrier()
; #define PG8_SCHED __builtin_amdgcn_sched_barrier(0)
; template <class Epi>
; __device__ __forceinline__ void gemm_phase(LAS unsigned char* lds, const Gemm g, const Sched& S, const Epi& E) {
;     ...
;             PG8_WAIT_V(8); PG8_WAIT_L(0); PG8_BAR; PG8_MMA(0, 0, At, B0); PG8_MMA(0, 1, At, B1); PG8_BAR; PG8_SCHED;
;             PG8_LDA(At, 0, 1); PG8_STAGE(PG8_SB(0, 0), b2, voffB); PG8_STAGE(PG8_SB(0, 1), b2 + hstepB, voffB); PG8_STAGE(PG8_SA(0, 0), a2, voffA);
.Lrx_p1_0_j:
	s_waitcnt lgkmcnt(0)
	s_cmp_eq_u32 s86, -2
	s_cbranch_scc1 .Lcz_p1_0
	s_barrier
	s_setprio 1
	s_waitcnt lgkmcnt(0)
	v_mfma_f32_16x16x32_bf16 v[126:129], v[156:159], v[188:191], v[126:129]
	v_mfma_f32_16x16x32_bf16 v[122:125], v[164:167], v[188:191], v[122:125]
	v_mfma_f32_16x16x32_bf16 v[110:113], v[156:159], v[200:203], v[110:113]
	v_mfma_f32_16x16x32_bf16 v[106:109], v[164:167], v[200:203], v[106:109]
	v_mfma_f32_16x16x32_bf16 v[94:97], v[156:159], v[208:211], v[94:97]
	v_mfma_f32_16x16x32_bf16 v[90:93], v[164:167], v[208:211], v[90:93]
	v_mfma_f32_16x16x32_bf16 v[78:81], v[156:159], v[216:219], v[78:81]
	v_mfma_f32_16x16x32_bf16 v[74:77], v[164:167], v[216:219], v[74:77]
	v_mfma_f32_16x16x32_bf16 v[126:129], v[160:163], v[192:195], v[126:129]
	v_mfma_f32_16x16x32_bf16 v[122:125], v[168:171], v[192:195], v[122:125]
	v_mfma_f32_16x16x32_bf16 v[110:113], v[160:163], v[204:207], v[110:113]
	v_mfma_f32_16x16x32_bf16 v[106:109], v[168:171], v[204:207], v[106:109]
	v_mfma_f32_16x16x32_bf16 v[94:97], v[160:163], v[212:215], v[94:97]
	v_mfma_f32_16x16x32_bf16 v[90:93], v[168:171], v[212:215], v[90:93]
	v_mfma_f32_16x16x32_bf16 v[78:81], v[160:163], v[220:223], v[78:81]
	v_mfma_f32_16x16x32_bf16 v[74:77], v[168:171], v[220:223], v[74:77]
	s_setprio 0
	s_setprio 1
	v_mfma_f32_16x16x32_bf16 v[118:121], v[172:175], v[188:191], v[118:121]
	v_mfma_f32_16x16x32_bf16 v[114:117], v[180:183], v[188:191], v[114:117]
	v_mfma_f32_16x16x32_bf16 v[102:105], v[172:175], v[200:203], v[102:105]
	v_mfma_f32_16x16x32_bf16 v[98:101], v[180:183], v[200:203], v[98:101]
	v_mfma_f32_16x16x32_bf16 v[86:89], v[172:175], v[208:211], v[86:89]
	v_mfma_f32_16x16x32_bf16 v[82:85], v[180:183], v[208:211], v[82:85]
	v_mfma_f32_16x16x32_bf16 v[70:73], v[172:175], v[216:219], v[70:73]
	v_mfma_f32_16x16x32_bf16 v[66:69], v[180:183], v[216:219], v[66:69]
	v_mfma_f32_16x16x32_bf16 v[118:121], v[176:179], v[192:195], v[118:121]
	v_mfma_f32_16x16x32_bf16 v[114:117], v[184:187], v[192:195], v[114:117]
	v_mfma_f32_16x16x32_bf16 v[102:105], v[176:179], v[204:207], v[102:105]
	v_mfma_f32_16x16x32_bf16 v[98:101], v[184:187], v[204:207], v[98:101]
	v_mfma_f32_16x16x32_bf16 v[86:89], v[176:179], v[212:215], v[86:89]
	v_mfma_f32_16x16x32_bf16 v[82:85], v[184:187], v[212:215], v[82:85]
	v_mfma_f32_16x16x32_bf16 v[70:73], v[176:179], v[220:223], v[70:73]
	v_mfma_f32_16x16x32_bf16 v[66:69], v[184:187], v[220:223], v[66:69]
.Lcz_p1_0_j:
	s_setprio 0
	s_barrier
	s_add_i32 s87, s72, s24
	v_lshl_add_u64 v[196:197], s[38:39], 0, v[132:133]
	s_mov_b32 m0, s87
	ds_read_b128 v[188:191], v155 offset:16384
	ds_read_b128 v[192:195], v155 offset:17408
	ds_read_b128 v[200:203], v155 offset:18432
	ds_read_b128 v[204:207], v155 offset:19456
	ds_read_b128 v[208:211], v155 offset:20480
	ds_read_b128 v[212:215], v155 offset:21504
	ds_read_b128 v[216:219], v155 offset:22528
	ds_read_b128 v[220:223], v155 offset:23552
	global_load_lds_dwordx4 v[196:197], off
	s_add_i32 m0, s87, 0x2000
	s_add_u32 s88, s38, 0x40000
	v_lshl_add_u64 v[224:225], s[38:39], 0, v[136:137]
	s_addc_u32 s89, s39, 0
	s_add_i32 s87, s73, s24
	global_load_lds_dwordx4 v[224:225], off
	v_lshl_add_u64 v[226:227], s[88:89], 0, v[132:133]
	s_mov_b32 m0, s87
	v_lshl_add_u64 v[228:229], s[40:41], 0, v[134:135]
	global_load_lds_dwordx4 v[226:227], off
	v_lshl_add_u64 v[226:227], s[88:89], 0, v[136:137]
	s_add_i32 m0, s87, 0x2000
	s_nop 0
	global_load_lds_dwordx4 v[226:227], off
	v_lshl_add_u64 v[226:227], s[40:41], 0, v[130:131]
	s_mov_b32 m0, s25
	s_nop 0
	global_load_lds_dwordx4 v[226:227], off
	s_mov_b32 m0, s31
	s_nop 0
	global_load_lds_dwordx4 v[228:229], off
	s_cmp_eq_u32 s98, 0
	s_cbranch_scc1 .Lrx_p1_1_n
	s_sub_u32 s98, s98, 1
	s_waitcnt vmcnt(16)
	s_branch .Lrx_p1_1_j

; #define PG8_STAGE(bufoff, gbase, voff) do { _Pragma("unroll") for (int _i = 0; _i < 2; ++_i) \
;         __builtin_amdgcn_global_load_lds((const unsigned*)((const char*)(gbase) + (voff)[_i]), (LAS unsigned*)(lds + (bufoff) + ldsw + _i * 8192), 16, 0, 0); } while (0)
; #define PG8_LDA(dst, b, h) do { _Pragma("unroll") for (int m = 0; m < 4; ++m) _Pragma("unroll") for (int k = 0; k < 2; ++k) dst[m][k] = *(const LAS bf16x8*)(lds + PG8_SA(b, h) + aoff + m * 2048 + k * 1024); } while (0)
; #define PG8_LDB(dst, b, h) do { _Pragma("unroll") for (int n = 0; n < 2; ++n) _Pragma("unroll") for (int k = 0; k < 2; ++k) dst[n][k] = *(const LAS bf16x8*)(lds + PG8_SB(b, h) + boff + n * 2048 + k * 1024); } while (0)
; #define PG8_MMA(ai, bj, At, Bt) do { __builtin_amdgcn_s_setprio(1); _Pragma("unroll") for (int m = 0; m < 4; ++m) _Pragma("unroll") for (int n = 0; n < 2; ++n) _Pragma("unroll") for (int k = 0; k < 2; ++k) \
;         acc[ai][bj][m][n] = __builtin_amdgcn_mfma_f32_16x16x32_bf16(Bt[n][k], At[m][k], acc[ai][bj][m][n], 0, 0, 0); __builtin_amdgcn_s_setprio(0); } while (0)
; #define PG8_WAIT_V(n) asm volatile("s_waitcnt vmcnt(" #n ")" ::: "memory")
; #define PG8_WAIT_L(n) asm volatile("s_waitcnt lgkmcnt(" #n ")" ::: "memory")
; #define PG8_BAR __builtin_amdgcn_s_barrier()
; #define PG8_SCHED __builtin_amdgcn_sched_barrier(0)
; template <class Epi>
; __device__ __forceinline__ void gemm_phase(LAS unsigned char* lds, const Gemm g, const Sched& S, const Epi& E) {
;     ...
;             PG8_WAIT_V(8); PG8_WAIT_L(0); PG8_BAR; PG8_MMA(1, 0, At, B0); PG8_MMA(1, 1, At, B1); PG8_BAR; PG8_SCHED;
;             PG8_LDB(B0, 1, 0); PG8_LDB(B1, 1, 1); PG8_SCHED; PG8_LDA(At, 1, 0); PG8_STAGE(PG8_SA(0, 1), a2 + hstepA, voffA);
;             PG8_WAIT_V(8); PG8_WAIT_L(0); PG8_BAR; PG8_MMA(0, 0, At, B0); PG8_MMA(0, 1, At, B1); PG8_BAR; PG8_SCHED;
.Lrx_p1_1_j:
	s_waitcnt lgkmcnt(0)
	s_cmp_eq_u32 s86, -2
	s_cbranch_scc1 .Lcz_p1_1
	s_barrier
	s_setprio 1
	s_waitcnt lgkmcnt(0)
	v_mfma_f32_16x16x32_bf16 v[62:65], v[156:159], v[188:191], v[62:65]
	v_mfma_f32_16x16x32_bf16 v[58:61], v[164:167], v[188:191], v[58:61]
	v_mfma_f32_16x16x32_bf16 v[46:49], v[156:159], v[200:203], v[46:49]
	v_mfma_f32_16x16x32_bf16 v[42:45], v[164:167], v[200:203], v[42:45]
	v_mfma_f32_16x16x32_bf16 v[30:33], v[156:159], v[208:211], v[30:33]
	v_mfma_f32_16x16x32_bf16 v[26:29], v[164:167], v[208:211], v[26:29]
	v_mfma_f32_16x16x32_bf16 v[14:17], v[156:159], v[216:219], v[14:17]
	v_mfma_f32_16x16x32_bf16 v[10:13], v[164:167], v[216:219], v[10:13]
	v_mfma_f32_16x16x32_bf16 v[62:65], v[160:163], v[192:195], v[62:65]
	v_mfma_f32_16x16x32_bf16 v[58:61], v[168:171], v[192:195], v[58:61]
	v_mfma_f32_16x16x32_bf16 v[46:49], v[160:163], v[204:207], v[46:49]
	v_mfma_f32_16x16x32_bf16 v[42:45], v[168:171], v[204:207], v[42:45]
	v_mfma_f32_16x16x32_bf16 v[30:33], v[160:163], v[212:215], v[30:33]
	v_mfma_f32_16x16x32_bf16 v[26:29], v[168:171], v[212:215], v[26:29]
	v_mfma_f32_16x16x32_bf16 v[14:17], v[160:163], v[220:223], v[14:17]
	v_mfma_f32_16x16x32_bf16 v[10:13], v[168:171], v[220:223], v[10:13]
	s_setprio 0
	s_setprio 1
	v_mfma_f32_16x16x32_bf16 v[54:57], v[172:175], v[188:191], v[54:57]
	v_mfma_f32_16x16x32_bf16 v[50:53], v[180:183], v[188:191], v[50:53]
	v_mfma_f32_16x16x32_bf16 v[38:41], v[172:175], v[200:203], v[38:41]
	v_mfma_f32_16x16x32_bf16 v[34:37], v[180:183], v[200:203], v[34:37]
	v_mfma_f32_16x16x32_bf16 v[22:25], v[172:175], v[208:211], v[22:25]
	v_mfma_f32_16x16x32_bf16 v[18:21], v[180:183], v[208:211], v[18:21]
	v_mfma_f32_16x16x32_bf16 v[6:9], v[172:175], v[216:219], v[6:9]
	v_mfma_f32_16x16x32_bf16 v[2:5], v[180:183], v[216:219], v[2:5]
	v_mfma_f32_16x16x32_bf16 v[54:57], v[176:179], v[192:195], v[54:57]
	v_mfma_f32_16x16x32_bf16 v[50:53], v[184:187], v[192:195], v[50:53]
	v_mfma_f32_16x16x32_bf16 v[38:41], v[176:179], v[204:207], v[38:41]
	v_mfma_f32_16x16x32_bf16 v[34:37], v[184:187], v[204:207], v[34:37]
	v_mfma_f32_16x16x32_bf16 v[22:25], v[176:179], v[212:215], v[22:25]
	v_mfma_f32_16x16x32_bf16 v[18:21], v[184:187], v[212:215], v[18:21]
	v_mfma_f32_16x16x32_bf16 v[6:9], v[176:179], v[220:223], v[6:9]
	v_mfma_f32_16x16x32_bf16 v[2:5], v[184:187], v[220:223], v[2:5]
.Lcz_p1_1_j:
	s_setprio 0
	s_barrier
	s_add_i32 s87, 0, 0x18000
	s_add_i32 s88, 0, 0x1c000
	v_add_u32_e32 v168, s87, v147
	v_add_u32_e32 v184, s88, v147
	ds_read_b128 v[156:159], v168
	ds_read_b128 v[160:163], v168 offset:1024
	ds_read_b128 v[164:167], v168 offset:2048
	ds_read_b128 v[168:171], v168 offset:3072
	ds_read_b128 v[172:175], v184
	ds_read_b128 v[176:179], v184 offset:1024
	ds_read_b128 v[180:183], v184 offset:2048
	ds_read_b128 v[184:187], v184 offset:3072
	s_add_u32 s40, s40, 0x40000
	s_addc_u32 s41, s41, 0
	s_mov_b32 m0, s52
	v_lshl_add_u64 v[230:231], s[40:41], 0, v[130:131]
	ds_read_b128 v[188:191], v155 offset:32768
	ds_read_b128 v[192:195], v155 offset:33792
	ds_read_b128 v[200:203], v155 offset:34816
	ds_read_b128 v[204:207], v155 offset:35840
	ds_read_b128 v[208:211], v155 offset:36864
	ds_read_b128 v[212:215], v155 offset:37888
	ds_read_b128 v[216:219], v155 offset:38912
	ds_read_b128 v[220:223], v155 offset:39936
	global_load_lds_dwordx4 v[230:231], off
	v_lshl_add_u64 v[230:231], s[40:41], 0, v[134:135]
	s_mov_b32 m0, s53
	s_nop 0
	global_load_lds_dwordx4 v[230:231], off
	s_waitcnt vmcnt(8)
	s_waitcnt lgkmcnt(0)
	s_barrier
	s_setprio 1
	s_waitcnt lgkmcnt(0)
	v_mfma_f32_16x16x32_bf16 v[126:129], v[156:159], v[188:191], v[126:129]
	v_mfma_f32_16x16x32_bf16 v[122:125], v[164:167], v[188:191], v[122:125]
	v_mfma_f32_16x16x32_bf16 v[110:113], v[156:159], v[200:203], v[110:113]
	v_mfma_f32_16x16x32_bf16 v[106:109], v[164:167], v[200:203], v[106:109]
	v_mfma_f32_16x16x32_bf16 v[94:97], v[156:159], v[208:211], v[94:97]
	v_mfma_f32_16x16x32_bf16 v[90:93], v[164:167], v[208:211], v[90:93]
	v_mfma_f32_16x16x32_bf16 v[78:81], v[156:159], v[216:219], v[78:81]
	v_mfma_f32_16x16x32_bf16 v[74:77], v[164:167], v[216:219], v[74:77]
	v_mfma_f32_16x16x32_bf16 v[126:129], v[160:163], v[192:195], v[126:129]
	v_mfma_f32_16x16x32_bf16 v[122:125], v[168:171], v[192:195], v[122:125]
	v_mfma_f32_16x16x32_bf16 v[110:113], v[160:163], v[204:207], v[110:113]
	v_mfma_f32_16x16x32_bf16 v[106:109], v[168:171], v[204:207], v[106:109]
	v_mfma_f32_16x16x32_bf16 v[94:97], v[160:163], v[212:215], v[94:97]
	v_mfma_f32_16x16x32_bf16 v[90:93], v[168:171], v[212:215], v[90:93]
	v_mfma_f32_16x16x32_bf16 v[78:81], v[160:163], v[220:223], v[78:81]
	v_mfma_f32_16x16x32_bf16 v[74:77], v[168:171], v[220:223], v[74:77]
	s_setprio 0
	s_setprio 1
	v_mfma_f32_16x16x32_bf16 v[118:121], v[172:175], v[188:191], v[118:121]
	v_mfma_f32_16x16x32_bf16 v[114:117], v[180:183], v[188:191], v[114:117]
	v_mfma_f32_16x16x32_bf16 v[102:105], v[172:175], v[200:203], v[102:105]
	v_mfma_f32_16x16x32_bf16 v[98:101], v[180:183], v[200:203], v[98:101]
	v_mfma_f32_16x16x32_bf16 v[86:89], v[172:175], v[208:211], v[86:89]
	v_mfma_f32_16x16x32_bf16 v[82:85], v[180:183], v[208:211], v[82:85]
	v_mfma_f32_16x16x32_bf16 v[70:73], v[172:175], v[216:219], v[70:73]
	v_mfma_f32_16x16x32_bf16 v[66:69], v[180:183], v[216:219], v[66:69]
	v_mfma_f32_16x16x32_bf16 v[118:121], v[176:179], v[192:195], v[118:121]
	v_mfma_f32_16x16x32_bf16 v[114:117], v[184:187], v[192:195], v[114:117]
	v_mfma_f32_16x16x32_bf16 v[102:105], v[176:179], v[204:207], v[102:105]
	v_mfma_f32_16x16x32_bf16 v[98:101], v[184:187], v[204:207], v[98:101]
	v_mfma_f32_16x16x32_bf16 v[86:89], v[176:179], v[212:215], v[86:89]
	v_mfma_f32_16x16x32_bf16 v[82:85], v[184:187], v[212:215], v[82:85]
	v_mfma_f32_16x16x32_bf16 v[70:73], v[176:179], v[220:223], v[70:73]
	v_mfma_f32_16x16x32_bf16 v[66:69], v[184:187], v[220:223], v[66:69]
	s_setprio 0
	s_barrier
; #define PG8_STAGE(bufoff, gbase, voff) do { _Pragma("unroll") for (int _i = 0; _i < 2; ++_i) \
;         __builtin_amdgcn_global_load_lds((const unsigned*)((const char*)(gbase) + (voff)[_i]), (LAS unsigned*)(lds + (bufoff) + ldsw + _i * 8192), 16, 0, 0); } while (0)
; #define PG8_LDA(dst, b, h) do { _Pragma("unroll") for (int m = 0; m < 4; ++m) _Pragma("unroll") for (int k = 0; k < 2; ++k) dst[m][k] = *(const LAS bf16x8*)(lds + PG8_SA(b, h) + aoff + m * 2048 + k * 1024); } while (0)
; #define PG8_MMA(ai, bj, At, Bt) do { __builtin_amdgcn_s_setprio(1); _Pragma("unroll") for (int m = 0; m < 4; ++m) _Pragma("unroll") for (int n = 0; n < 2; ++n) _Pragma("unroll") for (int k = 0; k < 2; ++k) \
;         acc[ai][bj][m][n] = __builtin_amdgcn_mfma_f32_16x16x32_bf16(Bt[n][k], At[m][k], acc[ai][bj][m][n], 0, 0, 0); __builtin_amdgcn_s_setprio(0); } while (0)
; #define PG8_WAIT_V(n) asm volatile("s_waitcnt vmcnt(" #n ")" ::: "memory")
; #define PG8_WAIT_L(n) asm volatile("s_waitcnt lgkmcnt(" #n ")" ::: "memory")
; #define PG8_BAR __builtin_amdgcn_s_barrier()
; #define PG8_SCHED __builtin_amdgcn_sched_barrier(0)
; template <class Epi>
; __device__ __forceinline__ void gemm_phase(LAS unsigned char* lds, const Gemm g, const Sched& S, const Epi& E) {
;     ...
;             PG8_WAIT_V(8); PG8_WAIT_L(0); PG8_BAR; PG8_MMA(0, 0, At, B0); PG8_MMA(0, 1, At, B1); PG8_BAR; PG8_SCHED;
;             PG8_LDA(At, 1, 1); PG8_STAGE(PG8_SB(1, 0), b3, voffB); PG8_STAGE(PG8_SB(1, 1), b3 + hstepB, voffB); PG8_STAGE(PG8_SA(1, 0), a3, voffA);
;             PG8_WAIT_V(8); PG8_WAIT_L(0); PG8_BAR; PG8_MMA(1, 0, At, B0); PG8_MMA(1, 1, At, B1); PG8_BAR; PG8_SCHED;
;         }
;         if (wr == 0) PG8_BAR;
	s_add_i32 s40, s87, s24
	v_lshl_add_u64 v[196:197], v[196:197], 0, s[6:7]
	s_mov_b32 m0, s40
	ds_read_b128 v[188:191], v155 offset:49152
	ds_read_b128 v[192:195], v155 offset:50176
	ds_read_b128 v[200:203], v155 offset:51200
	ds_read_b128 v[204:207], v155 offset:52224
	ds_read_b128 v[208:211], v155 offset:53248
	ds_read_b128 v[212:215], v155 offset:54272
	ds_read_b128 v[216:219], v155 offset:55296
	ds_read_b128 v[220:223], v155 offset:56320
	global_load_lds_dwordx4 v[196:197], off
	s_add_i32 m0, s40, 0x2000
	s_add_u32 s38, s38, 0x40080
	v_lshl_add_u64 v[196:197], v[224:225], 0, s[6:7]
	s_addc_u32 s39, s39, 0
	s_add_i32 s40, s88, s24
	global_load_lds_dwordx4 v[196:197], off
	v_lshl_add_u64 v[196:197], s[38:39], 0, v[132:133]
	s_mov_b32 m0, s40
	s_nop 0
	global_load_lds_dwordx4 v[196:197], off
	v_lshl_add_u64 v[196:197], s[38:39], 0, v[136:137]
	s_add_i32 m0, s40, 0x2000
	s_nop 0
	global_load_lds_dwordx4 v[196:197], off
	v_lshl_add_u64 v[196:197], v[226:227], 0, s[6:7]
	s_mov_b32 m0, s54
	s_nop 0
	global_load_lds_dwordx4 v[196:197], off
	v_lshl_add_u64 v[196:197], v[228:229], 0, s[6:7]
	s_mov_b32 m0, s55
	s_nop 0
	global_load_lds_dwordx4 v[196:197], off
	s_waitcnt vmcnt(8)
	s_waitcnt lgkmcnt(0)
	s_barrier
	s_setprio 1
	s_waitcnt lgkmcnt(0)
	v_mfma_f32_16x16x32_bf16 v[62:65], v[156:159], v[188:191], v[62:65]
	v_mfma_f32_16x16x32_bf16 v[58:61], v[164:167], v[188:191], v[58:61]
	v_mfma_f32_16x16x32_bf16 v[46:49], v[156:159], v[200:203], v[46:49]
	v_mfma_f32_16x16x32_bf16 v[42:45], v[164:167], v[200:203], v[42:45]
	v_mfma_f32_16x16x32_bf16 v[30:33], v[156:159], v[208:211], v[30:33]
	v_mfma_f32_16x16x32_bf16 v[26:29], v[164:167], v[208:211], v[26:29]
	v_mfma_f32_16x16x32_bf16 v[14:17], v[156:159], v[216:219], v[14:17]
	v_mfma_f32_16x16x32_bf16 v[10:13], v[164:167], v[216:219], v[10:13]
	v_mfma_f32_16x16x32_bf16 v[62:65], v[160:163], v[192:195], v[62:65]
	v_mfma_f32_16x16x32_bf16 v[58:61], v[168:171], v[192:195], v[58:61]
	v_mfma_f32_16x16x32_bf16 v[46:49], v[160:163], v[204:207], v[46:49]
	v_mfma_f32_16x16x32_bf16 v[42:45], v[168:171], v[204:207], v[42:45]
	v_mfma_f32_16x16x32_bf16 v[30:33], v[160:163], v[212:215], v[30:33]
	v_mfma_f32_16x16x32_bf16 v[26:29], v[168:171], v[212:215], v[26:29]
	v_mfma_f32_16x16x32_bf16 v[14:17], v[160:163], v[220:223], v[14:17]
	v_mfma_f32_16x16x32_bf16 v[10:13], v[168:171], v[220:223], v[10:13]
	s_setprio 0
	s_setprio 1
	v_mfma_f32_16x16x32_bf16 v[54:57], v[172:175], v[188:191], v[54:57]
	v_mfma_f32_16x16x32_bf16 v[50:53], v[180:183], v[188:191], v[50:53]
	v_mfma_f32_16x16x32_bf16 v[38:41], v[172:175], v[200:203], v[38:41]
	v_mfma_f32_16x16x32_bf16 v[34:37], v[180:183], v[200:203], v[34:37]
	v_mfma_f32_16x16x32_bf16 v[22:25], v[172:175], v[208:211], v[22:25]
	v_mfma_f32_16x16x32_bf16 v[18:21], v[180:183], v[208:211], v[18:21]
	v_mfma_f32_16x16x32_bf16 v[6:9], v[172:175], v[216:219], v[6:9]
	v_mfma_f32_16x16x32_bf16 v[2:5], v[180:183], v[216:219], v[2:5]
	v_mfma_f32_16x16x32_bf16 v[54:57], v[176:179], v[192:195], v[54:57]
	v_mfma_f32_16x16x32_bf16 v[50:53], v[184:187], v[192:195], v[50:53]
	v_mfma_f32_16x16x32_bf16 v[38:41], v[176:179], v[204:207], v[38:41]
	v_mfma_f32_16x16x32_bf16 v[34:37], v[184:187], v[204:207], v[34:37]
	v_mfma_f32_16x16x32_bf16 v[22:25], v[176:179], v[212:215], v[22:25]
	v_mfma_f32_16x16x32_bf16 v[18:21], v[184:187], v[212:215], v[18:21]
	v_mfma_f32_16x16x32_bf16 v[6:9], v[176:179], v[220:223], v[6:9]
	v_mfma_f32_16x16x32_bf16 v[2:5], v[184:187], v[220:223], v[2:5]
	s_setprio 0
	s_barrier
	s_add_i32 s86, s86, 2
	s_add_u32 s34, s34, 0x100
	s_addc_u32 s35, s35, 0
	s_add_u32 s84, s84, 0x100
	s_addc_u32 s85, s85, 0
	s_cmp_gt_u32 s86, 13
	s_cbranch_scc0 .LBB0_584
	s_and_b64 vcc, exec, s[8:9]
	s_cbranch_vccz .LBB0_587
	s_barrier

.Lcz_p1_0:
	s_barrier
	s_setprio 1
	s_waitcnt lgkmcnt(0)
	v_mfma_f32_16x16x32_bf16 v[126:129], v[156:159], v[188:191], 0
	v_mfma_f32_16x16x32_bf16 v[122:125], v[164:167], v[188:191], 0
	v_mfma_f32_16x16x32_bf16 v[110:113], v[156:159], v[200:203], 0
	v_mfma_f32_16x16x32_bf16 v[106:109], v[164:167], v[200:203], 0
	v_mfma_f32_16x16x32_bf16 v[94:97], v[156:159], v[208:211], 0
	v_mfma_f32_16x16x32_bf16 v[90:93], v[164:167], v[208:211], 0
	v_mfma_f32_16x16x32_bf16 v[78:81], v[156:159], v[216:219], 0
	v_mfma_f32_16x16x32_bf16 v[74:77], v[164:167], v[216:219], 0
	v_mfma_f32_16x16x32_bf16 v[126:129], v[160:163], v[192:195], v[126:129]
	v_mfma_f32_16x16x32_bf16 v[122:125], v[168:171], v[192:195], v[122:125]
	v_mfma_f32_16x16x32_bf16 v[110:113], v[160:163], v[204:207], v[110:113]
	v_mfma_f32_16x16x32_bf16 v[106:109], v[168:171], v[204:207], v[106:109]
	v_mfma_f32_16x16x32_bf16 v[94:97], v[160:163], v[212:215], v[94:97]
	v_mfma_f32_16x16x32_bf16 v[90:93], v[168:171], v[212:215], v[90:93]
	v_mfma_f32_16x16x32_bf16 v[78:81], v[160:163], v[220:223], v[78:81]
	v_mfma_f32_16x16x32_bf16 v[74:77], v[168:171], v[220:223], v[74:77]
	s_setprio 0
	s_setprio 1
	v_mfma_f32_16x16x32_bf16 v[118:121], v[172:175], v[188:191], 0
	v_mfma_f32_16x16x32_bf16 v[114:117], v[180:183], v[188:191], 0
	v_mfma_f32_16x16x32_bf16 v[102:105], v[172:175], v[200:203], 0
	v_mfma_f32_16x16x32_bf16 v[98:101], v[180:183], v[200:203], 0
	v_mfma_f32_16x16x32_bf16 v[86:89], v[172:175], v[208:211], 0
	v_mfma_f32_16x16x32_bf16 v[82:85], v[180:183], v[208:211], 0
	v_mfma_f32_16x16x32_bf16 v[70:73], v[172:175], v[216:219], 0
	v_mfma_f32_16x16x32_bf16 v[66:69], v[180:183], v[216:219], 0
	v_mfma_f32_16x16x32_bf16 v[118:121], v[176:179], v[192:195], v[118:121]
	v_mfma_f32_16x16x32_bf16 v[114:117], v[184:187], v[192:195], v[114:117]
	v_mfma_f32_16x16x32_bf16 v[102:105], v[176:179], v[204:207], v[102:105]
	v_mfma_f32_16x16x32_bf16 v[98:101], v[184:187], v[204:207], v[98:101]
	v_mfma_f32_16x16x32_bf16 v[86:89], v[176:179], v[212:215], v[86:89]
	v_mfma_f32_16x16x32_bf16 v[82:85], v[184:187], v[212:215], v[82:85]
	v_mfma_f32_16x16x32_bf16 v[70:73], v[176:179], v[220:223], v[70:73]
	v_mfma_f32_16x16x32_bf16 v[66:69], v[184:187], v[220:223], v[66:69]
	s_branch .Lcz_p1_0_j
.Lcz_p1_1:
	s_barrier
	s_setprio 1
	s_waitcnt lgkmcnt(0)
	v_mfma_f32_16x16x32_bf16 v[62:65], v[156:159], v[188:191], 0
	v_mfma_f32_16x16x32_bf16 v[58:61], v[164:167], v[188:191], 0
	v_mfma_f32_16x16x32_bf16 v[46:49], v[156:159], v[200:203], 0
	v_mfma_f32_16x16x32_bf16 v[42:45], v[164:167], v[200:203], 0
	v_mfma_f32_16x16x32_bf16 v[30:33], v[156:159], v[208:211], 0
	v_mfma_f32_16x16x32_bf16 v[26:29], v[164:167], v[208:211], 0
	v_mfma_f32_16x16x32_bf16 v[14:17], v[156:159], v[216:219], 0
	v_mfma_f32_16x16x32_bf16 v[10:13], v[164:167], v[216:219], 0
	v_mfma_f32_16x16x32_bf16 v[62:65], v[160:163], v[192:195], v[62:65]
	v_mfma_f32_16x16x32_bf16 v[58:61], v[168:171], v[192:195], v[58:61]
	v_mfma_f32_16x16x32_bf16 v[46:49], v[160:163], v[204:207], v[46:49]
	v_mfma_f32_16x16x32_bf16 v[42:45], v[168:171], v[204:207], v[42:45]
	v_mfma_f32_16x16x32_bf16 v[30:33], v[160:163], v[212:215], v[30:33]
	v_mfma_f32_16x16x32_bf16 v[26:29], v[168:171], v[212:215], v[26:29]
	v_mfma_f32_16x16x32_bf16 v[14:17], v[160:163], v[220:223], v[14:17]
	v_mfma_f32_16x16x32_bf16 v[10:13], v[168:171], v[220:223], v[10:13]
	s_setprio 0
	s_setprio 1
	v_mfma_f32_16x16x32_bf16 v[54:57], v[172:175], v[188:191], 0
	v_mfma_f32_16x16x32_bf16 v[50:53], v[180:183], v[188:191], 0
	v_mfma_f32_16x16x32_bf16 v[38:41], v[172:175], v[200:203], 0
	v_mfma_f32_16x16x32_bf16 v[34:37], v[180:183], v[200:203], 0
	v_mfma_f32_16x16x32_bf16 v[22:25], v[172:175], v[208:211], 0
	v_mfma_f32_16x16x32_bf16 v[18:21], v[180:183], v[208:211], 0
	v_mfma_f32_16x16x32_bf16 v[6:9], v[172:175], v[216:219], 0
	v_mfma_f32_16x16x32_bf16 v[2:5], v[180:183], v[216:219], 0
	v_mfma_f32_16x16x32_bf16 v[54:57], v[176:179], v[192:195], v[54:57]
	v_mfma_f32_16x16x32_bf16 v[50:53], v[184:187], v[192:195], v[50:53]
	v_mfma_f32_16x16x32_bf16 v[38:41], v[176:179], v[204:207], v[38:41]
	v_mfma_f32_16x16x32_bf16 v[34:37], v[184:187], v[204:207], v[34:37]
	v_mfma_f32_16x16x32_bf16 v[22:25], v[176:179], v[212:215], v[22:25]
	v_mfma_f32_16x16x32_bf16 v[18:21], v[184:187], v[212:215], v[18:21]
	v_mfma_f32_16x16x32_bf16 v[6:9], v[176:179], v[220:223], v[6:9]
	v_mfma_f32_16x16x32_bf16 v[2:5], v[184:187], v[220:223], v[2:5]
	s_branch .Lcz_p1_1_j

; #define PG8_STAGE(bufoff, gbase, voff) do { _Pragma("unroll") for (int _i = 0; _i < 2; ++_i) \
;         __builtin_amdgcn_global_load_lds((const unsigned*)((const char*)(gbase) + (voff)[_i]), (LAS unsigned*)(lds + (bufoff) + ldsw + _i * 8192), 16, 0, 0); } while (0)
; #define PG8_LDA(dst, b, h) do { _Pragma("unroll") for (int m = 0; m < 4; ++m) _Pragma("unroll") for (int k = 0; k < 2; ++k) dst[m][k] = *(const LAS bf16x8*)(lds + PG8_SA(b, h) + aoff + m * 2048 + k * 1024); } while (0)
; #define PG8_LDB(dst, b, h) do { _Pragma("unroll") for (int n = 0; n < 2; ++n) _Pragma("unroll") for (int k = 0; k < 2; ++k) dst[n][k] = *(const LAS bf16x8*)(lds + PG8_SB(b, h) + boff + n * 2048 + k * 1024); } while (0)
; #define PG8_WAIT_V(n) asm volatile("s_waitcnt vmcnt(" #n ")" ::: "memory")
; #define PG8_BAR __builtin_amdgcn_s_barrier()
; template <class Epi>
; __device__ __forceinline__ void gemm_phase(LAS unsigned char* lds, const Gemm g, const Sched& S, const Epi& E) {
;     ...
;         const bool has_next = S.next(ui + 1, nxt);
;         const char* nA = has_next ? (const char*)g.A + (size_t)nxt.pm * tstepA + (size_t)nxt.part * g.koff * 2 : cA; const char* nB = has_next ? (const char*)g.Bt + (size_t)nxt.pn * tstepB + (size_t)nxt.part * g.koff * 2 : cB;
;         for (int t = 0; t < nt; t += 2) {
;             const bool last = (t == nt - 2);
;             const char* a1 = cA + (size_t)(t + 1) * kstep;
;             const char* a2 = last ? nA : cA + (size_t)(t + 2) * kstep; const char* b2 = last ? nB : cB + (size_t)(t + 2) * kstep;
;             const char* a3 = a2 + kstep; const char* b3 = b2 + kstep;
;             PG8_LDB(B0, 0, 0); PG8_LDB(B1, 0, 1); PG8_SCHED; PG8_LDA(At, 0, 0); PG8_STAGE(PG8_SA(1, 1), a1 + hstepA, voffA);
;             PG8_WAIT_V(8); PG8_WAIT_L(0); PG8_BAR; PG8_MMA(0, 0, At, B0); PG8_MMA(0, 1, At, B1); PG8_BAR; PG8_SCHED;
;             PG8_LDA(At, 0, 1); PG8_STAGE(PG8_SB(0, 0), b2, voffB); PG8_STAGE(PG8_SB(0, 1), b2 + hstepB, voffB); PG8_STAGE(PG8_SA(0, 0), a2, voffA);
;     ...
;         if (!(Epi::KEEP_PART0 && cur.part == 0))
; #pragma unroll
;         for (int a = 0; a < 2; ++a)
; #pragma unroll
;             for (int b = 0; b < 2; ++b)
; #pragma unroll
;                 for (int m = 0; m < 4; ++m)
; #pragma unroll
;                     for (int n = 0; n < 2; ++n) acc[a][b][m][n] = (f32x4){0.f, 0.f, 0.f, 0.f};
;         cur = nxt; cA = nA; cB = nB; ++ui;
.LBB0_821:
	s_ashr_i32 s55, s54, 31
	s_lshl_b64 s[20:21], s[54:55], 19
	s_add_u32 s42, s88, s20
	s_addc_u32 s43, s89, s21
	s_and_b64 s[20:21], s[0:1], exec
	s_cselect_b32 s25, s43, s5
	s_cselect_b32 s55, s42, s4
	s_ashr_i32 s77, s76, 31
	s_lshl_b64 s[20:21], s[76:77], 19
	v_readlane_b32 s44, v252, 3
	v_readlane_b32 s45, v252, 4
	s_add_u32 s44, s44, s20
	s_addc_u32 s45, s45, s21
	s_and_b64 s[20:21], s[0:1], exec
	s_cselect_b32 s72, s45, s7
	s_cselect_b32 s73, s44, s6
	s_add_u32 s4, s4, 0x40080
	s_addc_u32 s5, s5, 0
	s_add_u32 s74, s6, 0x100
	s_addc_u32 s75, s7, 0
	s_mov_b32 s77, -2
.LBB0_822:
	ds_read_b128 v[130:133], v210
	ds_read_b128 v[134:137], v210 offset:1024
	ds_read_b128 v[138:141], v210 offset:2048
	ds_read_b128 v[142:145], v210 offset:3072
	ds_read_b128 v[146:149], v211
	ds_read_b128 v[150:153], v211 offset:1024
	ds_read_b128 v[180:183], v211 offset:2048
	ds_read_b128 v[184:187], v211 offset:3072
	s_add_u32 s6, s4, 0xfffc0080
	s_addc_u32 s7, s5, -1
	s_cmp_eq_u32 s77, 12
	s_cselect_b32 s21, s25, s7
	s_cselect_b32 s20, s55, s6
	s_cselect_b32 s7, s72, s75
	s_cselect_b32 s6, s73, s74
	v_lshl_add_u64 v[240:241], s[4:5], 0, v[172:173]
	s_add_i32 m0, s11, 0xc000
	ds_read_b128 v[188:191], v212
	ds_read_b128 v[192:195], v212 offset:1024
	ds_read_b128 v[216:219], v212 offset:2048
	ds_read_b128 v[220:223], v212 offset:3072
	ds_read_b128 v[224:227], v212 offset:4096
	ds_read_b128 v[228:231], v212 offset:5120
	ds_read_b128 v[232:235], v212 offset:6144
	ds_read_b128 v[236:239], v212 offset:7168
	global_load_lds_dwordx4 v[240:241], off
	v_lshl_add_u64 v[240:241], s[4:5], 0, v[174:175]
	s_add_i32 m0, s11, 0xe000
	s_nop 0
	global_load_lds_dwordx4 v[240:241], off
	s_waitcnt vmcnt(8)
	s_waitcnt lgkmcnt(0)
	s_cmp_eq_u32 s77, -2
	s_cbranch_scc1 .Lcz_p3_0
	s_barrier
	s_setprio 1
	s_waitcnt lgkmcnt(0)
	v_mfma_f32_16x16x32_bf16 v[126:129], v[130:133], v[188:191], v[126:129]
	v_mfma_f32_16x16x32_bf16 v[122:125], v[138:141], v[188:191], v[122:125]
	v_mfma_f32_16x16x32_bf16 v[110:113], v[130:133], v[216:219], v[110:113]
	v_mfma_f32_16x16x32_bf16 v[106:109], v[138:141], v[216:219], v[106:109]
	v_mfma_f32_16x16x32_bf16 v[94:97], v[130:133], v[224:227], v[94:97]
	v_mfma_f32_16x16x32_bf16 v[90:93], v[138:141], v[224:227], v[90:93]
	v_mfma_f32_16x16x32_bf16 v[78:81], v[130:133], v[232:235], v[78:81]
	v_mfma_f32_16x16x32_bf16 v[74:77], v[138:141], v[232:235], v[74:77]
	v_mfma_f32_16x16x32_bf16 v[126:129], v[134:137], v[192:195], v[126:129]
	v_mfma_f32_16x16x32_bf16 v[122:125], v[142:145], v[192:195], v[122:125]
	v_mfma_f32_16x16x32_bf16 v[110:113], v[134:137], v[220:223], v[110:113]
	v_mfma_f32_16x16x32_bf16 v[106:109], v[142:145], v[220:223], v[106:109]
	v_mfma_f32_16x16x32_bf16 v[94:97], v[134:137], v[228:231], v[94:97]
	v_mfma_f32_16x16x32_bf16 v[90:93], v[142:145], v[228:231], v[90:93]
	v_mfma_f32_16x16x32_bf16 v[78:81], v[134:137], v[236:239], v[78:81]
	v_mfma_f32_16x16x32_bf16 v[74:77], v[142:145], v[236:239], v[74:77]
	s_setprio 0
	s_setprio 1
	v_mfma_f32_16x16x32_bf16 v[118:121], v[146:149], v[188:191], v[118:121]
	v_mfma_f32_16x16x32_bf16 v[114:117], v[180:183], v[188:191], v[114:117]
	v_mfma_f32_16x16x32_bf16 v[102:105], v[146:149], v[216:219], v[102:105]
	v_mfma_f32_16x16x32_bf16 v[98:101], v[180:183], v[216:219], v[98:101]
	v_mfma_f32_16x16x32_bf16 v[86:89], v[146:149], v[224:227], v[86:89]
	v_mfma_f32_16x16x32_bf16 v[82:85], v[180:183], v[224:227], v[82:85]
	v_mfma_f32_16x16x32_bf16 v[70:73], v[146:149], v[232:235], v[70:73]
	v_mfma_f32_16x16x32_bf16 v[66:69], v[180:183], v[232:235], v[66:69]
	v_mfma_f32_16x16x32_bf16 v[118:121], v[150:153], v[192:195], v[118:121]
	v_mfma_f32_16x16x32_bf16 v[114:117], v[184:187], v[192:195], v[114:117]
	v_mfma_f32_16x16x32_bf16 v[102:105], v[150:153], v[220:223], v[102:105]
	v_mfma_f32_16x16x32_bf16 v[98:101], v[184:187], v[220:223], v[98:101]
	v_mfma_f32_16x16x32_bf16 v[86:89], v[150:153], v[228:231], v[86:89]
	v_mfma_f32_16x16x32_bf16 v[82:85], v[184:187], v[228:231], v[82:85]
	v_mfma_f32_16x16x32_bf16 v[70:73], v[150:153], v[236:239], v[70:73]
	v_mfma_f32_16x16x32_bf16 v[66:69], v[184:187], v[236:239], v[66:69]
.Lcz_p3_0_j:
	s_setprio 0
	s_barrier
	s_add_i32 s82, s19, s78
	v_lshl_add_u64 v[240:241], s[6:7], 0, v[156:157]
	s_mov_b32 m0, s82
	ds_read_b128 v[188:191], v212 offset:16384
	ds_read_b128 v[192:195], v212 offset:17408
	ds_read_b128 v[216:219], v212 offset:18432
	ds_read_b128 v[220:223], v212 offset:19456
	ds_read_b128 v[224:227], v212 offset:20480
	ds_read_b128 v[228:231], v212 offset:21504
	ds_read_b128 v[232:235], v212 offset:22528
	ds_read_b128 v[236:239], v212 offset:23552
	global_load_lds_dwordx4 v[240:241], off
	s_add_i32 m0, s82, 0x2000
	s_add_u32 s82, s6, 0x40000
	v_lshl_add_u64 v[242:243], s[6:7], 0, v[160:161]
	s_addc_u32 s83, s7, 0
	s_add_i32 s86, s22, s78
	global_load_lds_dwordx4 v[242:243], off
	v_lshl_add_u64 v[244:245], s[82:83], 0, v[156:157]
	s_mov_b32 m0, s86
	v_lshl_add_u64 v[246:247], s[20:21], 0, v[158:159]
	global_load_lds_dwordx4 v[244:245], off
	v_lshl_add_u64 v[244:245], s[82:83], 0, v[160:161]
	s_add_i32 m0, s86, 0x2000
	s_nop 0
	global_load_lds_dwordx4 v[244:245], off
	v_lshl_add_u64 v[244:245], s[20:21], 0, v[154:155]
	s_mov_b32 m0, s11
	s_nop 0
	global_load_lds_dwordx4 v[244:245], off
	s_mov_b32 m0, s31
	s_nop 0
	global_load_lds_dwordx4 v[246:247], off
	s_waitcnt vmcnt(8)
	s_waitcnt lgkmcnt(0)
	s_cmp_eq_u32 s77, -2
	s_cbranch_scc1 .Lcz_p3_1
	s_barrier
; #define PG8_STAGE(bufoff, gbase, voff) do { _Pragma("unroll") for (int _i = 0; _i < 2; ++_i) \
;         __builtin_amdgcn_global_load_lds((const unsigned*)((const char*)(gbase) + (voff)[_i]), (LAS unsigned*)(lds + (bufoff) + ldsw + _i * 8192), 16, 0, 0); } while (0)
; #define PG8_LDA(dst, b, h) do { _Pragma("unroll") for (int m = 0; m < 4; ++m) _Pragma("unroll") for (int k = 0; k < 2; ++k) dst[m][k] = *(const LAS bf16x8*)(lds + PG8_SA(b, h) + aoff + m * 2048 + k * 1024); } while (0)
; #define PG8_LDB(dst, b, h) do { _Pragma("unroll") for (int n = 0; n < 2; ++n) _Pragma("unroll") for (int k = 0; k < 2; ++k) dst[n][k] = *(const LAS bf16x8*)(lds + PG8_SB(b, h) + boff + n * 2048 + k * 1024); } while (0)
; #define PG8_MMA(ai, bj, At, Bt) do { __builtin_amdgcn_s_setprio(1); _Pragma("unroll") for (int m = 0; m < 4; ++m) _Pragma("unroll") for (int n = 0; n < 2; ++n) _Pragma("unroll") for (int k = 0; k < 2; ++k) \
;         acc[ai][bj][m][n] = __builtin_amdgcn_mfma_f32_16x16x32_bf16(Bt[n][k], At[m][k], acc[ai][bj][m][n], 0, 0, 0); __builtin_amdgcn_s_setprio(0); } while (0)
; #define PG8_WAIT_V(n) asm volatile("s_waitcnt vmcnt(" #n ")" ::: "memory")
; #define PG8_WAIT_L(n) asm volatile("s_waitcnt lgkmcnt(" #n ")" ::: "memory")
; #define PG8_BAR __builtin_amdgcn_s_barrier()
; #define PG8_SCHED __builtin_amdgcn_sched_barrier(0)
; template <class Epi>
; __device__ __forceinline__ void gemm_phase(LAS unsigned char* lds, const Gemm g, const Sched& S, const Epi& E) {
;     ...
;             PG8_WAIT_V(8); PG8_WAIT_L(0); PG8_BAR; PG8_MMA(1, 0, At, B0); PG8_MMA(1, 1, At, B1); PG8_BAR; PG8_SCHED;
;             PG8_LDB(B0, 1, 0); PG8_LDB(B1, 1, 1); PG8_SCHED; PG8_LDA(At, 1, 0); PG8_STAGE(PG8_SA(0, 1), a2 + hstepA, voffA);
;             PG8_WAIT_V(8); PG8_WAIT_L(0); PG8_BAR; PG8_MMA(0, 0, At, B0); PG8_MMA(0, 1, At, B1); PG8_BAR; PG8_SCHED;
	s_setprio 1
	s_waitcnt lgkmcnt(0)
	v_mfma_f32_16x16x32_bf16 v[62:65], v[130:133], v[188:191], v[62:65]
	v_mfma_f32_16x16x32_bf16 v[58:61], v[138:141], v[188:191], v[58:61]
	v_mfma_f32_16x16x32_bf16 v[46:49], v[130:133], v[216:219], v[46:49]
	v_mfma_f32_16x16x32_bf16 v[42:45], v[138:141], v[216:219], v[42:45]
	v_mfma_f32_16x16x32_bf16 v[30:33], v[130:133], v[224:227], v[30:33]
	v_mfma_f32_16x16x32_bf16 v[26:29], v[138:141], v[224:227], v[26:29]
	v_mfma_f32_16x16x32_bf16 v[14:17], v[130:133], v[232:235], v[14:17]
	v_mfma_f32_16x16x32_bf16 v[10:13], v[138:141], v[232:235], v[10:13]
	v_mfma_f32_16x16x32_bf16 v[62:65], v[134:137], v[192:195], v[62:65]
	v_mfma_f32_16x16x32_bf16 v[58:61], v[142:145], v[192:195], v[58:61]
	v_mfma_f32_16x16x32_bf16 v[46:49], v[134:137], v[220:223], v[46:49]
	v_mfma_f32_16x16x32_bf16 v[42:45], v[142:145], v[220:223], v[42:45]
	v_mfma_f32_16x16x32_bf16 v[30:33], v[134:137], v[228:231], v[30:33]
	v_mfma_f32_16x16x32_bf16 v[26:29], v[142:145], v[228:231], v[26:29]
	v_mfma_f32_16x16x32_bf16 v[14:17], v[134:137], v[236:239], v[14:17]
	v_mfma_f32_16x16x32_bf16 v[10:13], v[142:145], v[236:239], v[10:13]
	s_setprio 0
	s_setprio 1
	v_mfma_f32_16x16x32_bf16 v[54:57], v[146:149], v[188:191], v[54:57]
	v_mfma_f32_16x16x32_bf16 v[50:53], v[180:183], v[188:191], v[50:53]
	v_mfma_f32_16x16x32_bf16 v[38:41], v[146:149], v[216:219], v[38:41]
	v_mfma_f32_16x16x32_bf16 v[34:37], v[180:183], v[216:219], v[34:37]
	v_mfma_f32_16x16x32_bf16 v[22:25], v[146:149], v[224:227], v[22:25]
	v_mfma_f32_16x16x32_bf16 v[18:21], v[180:183], v[224:227], v[18:21]
	v_mfma_f32_16x16x32_bf16 v[6:9], v[146:149], v[232:235], v[6:9]
	v_mfma_f32_16x16x32_bf16 v[2:5], v[180:183], v[232:235], v[2:5]
	v_mfma_f32_16x16x32_bf16 v[54:57], v[150:153], v[192:195], v[54:57]
	v_mfma_f32_16x16x32_bf16 v[50:53], v[184:187], v[192:195], v[50:53]
	v_mfma_f32_16x16x32_bf16 v[38:41], v[150:153], v[220:223], v[38:41]
	v_mfma_f32_16x16x32_bf16 v[34:37], v[184:187], v[220:223], v[34:37]
	v_mfma_f32_16x16x32_bf16 v[22:25], v[150:153], v[228:231], v[22:25]
	v_mfma_f32_16x16x32_bf16 v[18:21], v[184:187], v[228:231], v[18:21]
	v_mfma_f32_16x16x32_bf16 v[6:9], v[150:153], v[236:239], v[6:9]
	v_mfma_f32_16x16x32_bf16 v[2:5], v[184:187], v[236:239], v[2:5]
.Lcz_p3_1_j:
	s_setprio 0
	s_barrier
	s_add_i32 s82, 0, 0x18000
	s_add_i32 s83, 0, 0x1c000
	v_add_u32_e32 v142, s82, v196
	v_add_u32_e32 v162, s83, v196
	ds_read_b128 v[130:133], v142
	ds_read_b128 v[134:137], v142 offset:1024
	ds_read_b128 v[138:141], v142 offset:2048
	ds_read_b128 v[142:145], v142 offset:3072
	ds_read_b128 v[146:149], v162
	ds_read_b128 v[150:153], v162 offset:1024
	ds_read_b128 v[180:183], v162 offset:2048
	ds_read_b128 v[184:187], v162 offset:3072
	s_add_u32 s20, s20, 0x40000
	s_addc_u32 s21, s21, 0
	s_mov_b32 m0, s79
	v_lshl_add_u64 v[248:249], s[20:21], 0, v[154:155]
	ds_read_b128 v[188:191], v212 offset:32768
	ds_read_b128 v[192:195], v212 offset:33792
	ds_read_b128 v[216:219], v212 offset:34816
	ds_read_b128 v[220:223], v212 offset:35840
	ds_read_b128 v[224:227], v212 offset:36864
	ds_read_b128 v[228:231], v212 offset:37888
	ds_read_b128 v[232:235], v212 offset:38912
	ds_read_b128 v[236:239], v212 offset:39936
	global_load_lds_dwordx4 v[248:249], off
	v_lshl_add_u64 v[248:249], s[20:21], 0, v[158:159]
	s_mov_b32 m0, s18
	s_nop 0
	global_load_lds_dwordx4 v[248:249], off
	s_waitcnt vmcnt(8)
	s_waitcnt lgkmcnt(0)
	s_barrier
	s_setprio 1
	s_waitcnt lgkmcnt(0)
	v_mfma_f32_16x16x32_bf16 v[126:129], v[130:133], v[188:191], v[126:129]
	v_mfma_f32_16x16x32_bf16 v[122:125], v[138:141], v[188:191], v[122:125]
	v_mfma_f32_16x16x32_bf16 v[110:113], v[130:133], v[216:219], v[110:113]
	v_mfma_f32_16x16x32_bf16 v[106:109], v[138:141], v[216:219], v[106:109]
	v_mfma_f32_16x16x32_bf16 v[94:97], v[130:133], v[224:227], v[94:97]
	v_mfma_f32_16x16x32_bf16 v[90:93], v[138:141], v[224:227], v[90:93]
	v_mfma_f32_16x16x32_bf16 v[78:81], v[130:133], v[232:235], v[78:81]
	v_mfma_f32_16x16x32_bf16 v[74:77], v[138:141], v[232:235], v[74:77]
	v_mfma_f32_16x16x32_bf16 v[126:129], v[134:137], v[192:195], v[126:129]
	v_mfma_f32_16x16x32_bf16 v[122:125], v[142:145], v[192:195], v[122:125]
	v_mfma_f32_16x16x32_bf16 v[110:113], v[134:137], v[220:223], v[110:113]
	v_mfma_f32_16x16x32_bf16 v[106:109], v[142:145], v[220:223], v[106:109]
	v_mfma_f32_16x16x32_bf16 v[94:97], v[134:137], v[228:231], v[94:97]
	v_mfma_f32_16x16x32_bf16 v[90:93], v[142:145], v[228:231], v[90:93]
	v_mfma_f32_16x16x32_bf16 v[78:81], v[134:137], v[236:239], v[78:81]
	v_mfma_f32_16x16x32_bf16 v[74:77], v[142:145], v[236:239], v[74:77]
	s_setprio 0
	s_setprio 1
	v_mfma_f32_16x16x32_bf16 v[118:121], v[146:149], v[188:191], v[118:121]
	v_mfma_f32_16x16x32_bf16 v[114:117], v[180:183], v[188:191], v[114:117]
	v_mfma_f32_16x16x32_bf16 v[102:105], v[146:149], v[216:219], v[102:105]
	v_mfma_f32_16x16x32_bf16 v[98:101], v[180:183], v[216:219], v[98:101]
	v_mfma_f32_16x16x32_bf16 v[86:89], v[146:149], v[224:227], v[86:89]
	v_mfma_f32_16x16x32_bf16 v[82:85], v[180:183], v[224:227], v[82:85]
	v_mfma_f32_16x16x32_bf16 v[70:73], v[146:149], v[232:235], v[70:73]
	v_mfma_f32_16x16x32_bf16 v[66:69], v[180:183], v[232:235], v[66:69]
	v_mfma_f32_16x16x32_bf16 v[118:121], v[150:153], v[192:195], v[118:121]
	v_mfma_f32_16x16x32_bf16 v[114:117], v[184:187], v[192:195], v[114:117]
	v_mfma_f32_16x16x32_bf16 v[102:105], v[150:153], v[220:223], v[102:105]
	v_mfma_f32_16x16x32_bf16 v[98:101], v[184:187], v[220:223], v[98:101]
	v_mfma_f32_16x16x32_bf16 v[86:89], v[150:153], v[228:231], v[86:89]
	v_mfma_f32_16x16x32_bf16 v[82:85], v[184:187], v[228:231], v[82:85]
	v_mfma_f32_16x16x32_bf16 v[70:73], v[150:153], v[236:239], v[70:73]
	v_mfma_f32_16x16x32_bf16 v[66:69], v[184:187], v[236:239], v[66:69]
	s_setprio 0
	s_barrier
; #define PG8_STAGE(bufoff, gbase, voff) do { _Pragma("unroll") for (int _i = 0; _i < 2; ++_i) \
;         __builtin_amdgcn_global_load_lds((const unsigned*)((const char*)(gbase) + (voff)[_i]), (LAS unsigned*)(lds + (bufoff) + ldsw + _i * 8192), 16, 0, 0); } while (0)
; #define PG8_LDA(dst, b, h) do { _Pragma("unroll") for (int m = 0; m < 4; ++m) _Pragma("unroll") for (int k = 0; k < 2; ++k) dst[m][k] = *(const LAS bf16x8*)(lds + PG8_SA(b, h) + aoff + m * 2048 + k * 1024); } while (0)
; #define PG8_MMA(ai, bj, At, Bt) do { __builtin_amdgcn_s_setprio(1); _Pragma("unroll") for (int m = 0; m < 4; ++m) _Pragma("unroll") for (int n = 0; n < 2; ++n) _Pragma("unroll") for (int k = 0; k < 2; ++k) \
;         acc[ai][bj][m][n] = __builtin_amdgcn_mfma_f32_16x16x32_bf16(Bt[n][k], At[m][k], acc[ai][bj][m][n], 0, 0, 0); __builtin_amdgcn_s_setprio(0); } while (0)
; #define PG8_WAIT_V(n) asm volatile("s_waitcnt vmcnt(" #n ")" ::: "memory")
; #define PG8_WAIT_L(n) asm volatile("s_waitcnt lgkmcnt(" #n ")" ::: "memory")
; #define PG8_BAR __builtin_amdgcn_s_barrier()
; #define PG8_SCHED __builtin_amdgcn_sched_barrier(0)
; template <class Epi>
; __device__ __forceinline__ void gemm_phase(LAS unsigned char* lds, const Gemm g, const Sched& S, const Epi& E) {
;     ...
;             PG8_WAIT_V(8); PG8_WAIT_L(0); PG8_BAR; PG8_MMA(0, 0, At, B0); PG8_MMA(0, 1, At, B1); PG8_BAR; PG8_SCHED;
;             PG8_LDA(At, 1, 1); PG8_STAGE(PG8_SB(1, 0), b3, voffB); PG8_STAGE(PG8_SB(1, 1), b3 + hstepB, voffB); PG8_STAGE(PG8_SA(1, 0), a3, voffA);
;             PG8_WAIT_V(8); PG8_WAIT_L(0); PG8_BAR; PG8_MMA(1, 0, At, B0); PG8_MMA(1, 1, At, B1); PG8_BAR; PG8_SCHED;
;         }
;         if (wr == 0) PG8_BAR;
	s_add_i32 s20, s82, s78
	v_lshl_add_u64 v[240:241], v[240:241], 0, s[26:27]
	s_mov_b32 m0, s20
	ds_read_b128 v[188:191], v212 offset:49152
	ds_read_b128 v[192:195], v212 offset:50176
	ds_read_b128 v[216:219], v212 offset:51200
	ds_read_b128 v[220:223], v212 offset:52224
	ds_read_b128 v[224:227], v212 offset:53248
	ds_read_b128 v[228:231], v212 offset:54272
	ds_read_b128 v[232:235], v212 offset:55296
	ds_read_b128 v[236:239], v212 offset:56320
	global_load_lds_dwordx4 v[240:241], off
	s_add_i32 m0, s20, 0x2000
	s_add_u32 s6, s6, 0x40080
	v_lshl_add_u64 v[240:241], v[242:243], 0, s[26:27]
	s_addc_u32 s7, s7, 0
	s_add_i32 s20, s83, s78
	global_load_lds_dwordx4 v[240:241], off
	v_lshl_add_u64 v[240:241], s[6:7], 0, v[156:157]
	s_mov_b32 m0, s20
	s_nop 0
	global_load_lds_dwordx4 v[240:241], off
	v_lshl_add_u64 v[240:241], s[6:7], 0, v[160:161]
	s_add_i32 m0, s20, 0x2000
	s_nop 0
	global_load_lds_dwordx4 v[240:241], off
	v_lshl_add_u64 v[240:241], v[244:245], 0, s[26:27]
	s_mov_b32 m0, s84
	s_nop 0
	global_load_lds_dwordx4 v[240:241], off
	v_lshl_add_u64 v[240:241], v[246:247], 0, s[26:27]
	s_mov_b32 m0, s85
	s_nop 0
	global_load_lds_dwordx4 v[240:241], off
	s_waitcnt vmcnt(8)
	s_waitcnt lgkmcnt(0)
	s_barrier
	s_setprio 1
	s_waitcnt lgkmcnt(0)
	v_mfma_f32_16x16x32_bf16 v[62:65], v[130:133], v[188:191], v[62:65]
	v_mfma_f32_16x16x32_bf16 v[58:61], v[138:141], v[188:191], v[58:61]
	v_mfma_f32_16x16x32_bf16 v[46:49], v[130:133], v[216:219], v[46:49]
	v_mfma_f32_16x16x32_bf16 v[42:45], v[138:141], v[216:219], v[42:45]
	v_mfma_f32_16x16x32_bf16 v[30:33], v[130:133], v[224:227], v[30:33]
	v_mfma_f32_16x16x32_bf16 v[26:29], v[138:141], v[224:227], v[26:29]
	v_mfma_f32_16x16x32_bf16 v[14:17], v[130:133], v[232:235], v[14:17]
	v_mfma_f32_16x16x32_bf16 v[10:13], v[138:141], v[232:235], v[10:13]
	v_mfma_f32_16x16x32_bf16 v[62:65], v[134:137], v[192:195], v[62:65]
	v_mfma_f32_16x16x32_bf16 v[58:61], v[142:145], v[192:195], v[58:61]
	v_mfma_f32_16x16x32_bf16 v[46:49], v[134:137], v[220:223], v[46:49]
	v_mfma_f32_16x16x32_bf16 v[42:45], v[142:145], v[220:223], v[42:45]
	v_mfma_f32_16x16x32_bf16 v[30:33], v[134:137], v[228:231], v[30:33]
	v_mfma_f32_16x16x32_bf16 v[26:29], v[142:145], v[228:231], v[26:29]
	v_mfma_f32_16x16x32_bf16 v[14:17], v[134:137], v[236:239], v[14:17]
	v_mfma_f32_16x16x32_bf16 v[10:13], v[142:145], v[236:239], v[10:13]
	s_setprio 0
	s_setprio 1
	v_mfma_f32_16x16x32_bf16 v[54:57], v[146:149], v[188:191], v[54:57]
	v_mfma_f32_16x16x32_bf16 v[50:53], v[180:183], v[188:191], v[50:53]
	v_mfma_f32_16x16x32_bf16 v[38:41], v[146:149], v[216:219], v[38:41]
	v_mfma_f32_16x16x32_bf16 v[34:37], v[180:183], v[216:219], v[34:37]
	v_mfma_f32_16x16x32_bf16 v[22:25], v[146:149], v[224:227], v[22:25]
	v_mfma_f32_16x16x32_bf16 v[18:21], v[180:183], v[224:227], v[18:21]
	v_mfma_f32_16x16x32_bf16 v[6:9], v[146:149], v[232:235], v[6:9]
	v_mfma_f32_16x16x32_bf16 v[2:5], v[180:183], v[232:235], v[2:5]
	v_mfma_f32_16x16x32_bf16 v[54:57], v[150:153], v[192:195], v[54:57]
	v_mfma_f32_16x16x32_bf16 v[50:53], v[184:187], v[192:195], v[50:53]
	v_mfma_f32_16x16x32_bf16 v[38:41], v[150:153], v[220:223], v[38:41]
	v_mfma_f32_16x16x32_bf16 v[34:37], v[184:187], v[220:223], v[34:37]
	v_mfma_f32_16x16x32_bf16 v[22:25], v[150:153], v[228:231], v[22:25]
	v_mfma_f32_16x16x32_bf16 v[18:21], v[184:187], v[228:231], v[18:21]
	v_mfma_f32_16x16x32_bf16 v[6:9], v[150:153], v[236:239], v[6:9]
	v_mfma_f32_16x16x32_bf16 v[2:5], v[184:187], v[236:239], v[2:5]
	s_setprio 0
	s_barrier
	s_add_i32 s77, s77, 2
	s_add_u32 s4, s4, 0x100
	s_addc_u32 s5, s5, 0
	s_add_u32 s74, s74, 0x100
	s_addc_u32 s75, s75, 0
	s_cmp_gt_u32 s77, 13
	s_cbranch_scc0 .LBB0_822
	s_and_b64 vcc, exec, s[28:29]
	s_cbranch_vccz .LBB0_825
	s_barrier

.Lcz_p3_0:
	s_barrier
	s_setprio 1
	s_waitcnt lgkmcnt(0)
	v_mfma_f32_16x16x32_bf16 v[126:129], v[130:133], v[188:191], 0
	v_mfma_f32_16x16x32_bf16 v[122:125], v[138:141], v[188:191], 0
	v_mfma_f32_16x16x32_bf16 v[110:113], v[130:133], v[216:219], 0
	v_mfma_f32_16x16x32_bf16 v[106:109], v[138:141], v[216:219], 0
	v_mfma_f32_16x16x32_bf16 v[94:97], v[130:133], v[224:227], 0
	v_mfma_f32_16x16x32_bf16 v[90:93], v[138:141], v[224:227], 0
	v_mfma_f32_16x16x32_bf16 v[78:81], v[130:133], v[232:235], 0
	v_mfma_f32_16x16x32_bf16 v[74:77], v[138:141], v[232:235], 0
	v_mfma_f32_16x16x32_bf16 v[126:129], v[134:137], v[192:195], v[126:129]
	v_mfma_f32_16x16x32_bf16 v[122:125], v[142:145], v[192:195], v[122:125]
	v_mfma_f32_16x16x32_bf16 v[110:113], v[134:137], v[220:223], v[110:113]
	v_mfma_f32_16x16x32_bf16 v[106:109], v[142:145], v[220:223], v[106:109]
	v_mfma_f32_16x16x32_bf16 v[94:97], v[134:137], v[228:231], v[94:97]
	v_mfma_f32_16x16x32_bf16 v[90:93], v[142:145], v[228:231], v[90:93]
	v_mfma_f32_16x16x32_bf16 v[78:81], v[134:137], v[236:239], v[78:81]
	v_mfma_f32_16x16x32_bf16 v[74:77], v[142:145], v[236:239], v[74:77]
	s_setprio 0
	s_setprio 1
	v_mfma_f32_16x16x32_bf16 v[118:121], v[146:149], v[188:191], 0
	v_mfma_f32_16x16x32_bf16 v[114:117], v[180:183], v[188:191], 0
	v_mfma_f32_16x16x32_bf16 v[102:105], v[146:149], v[216:219], 0
	v_mfma_f32_16x16x32_bf16 v[98:101], v[180:183], v[216:219], 0
	v_mfma_f32_16x16x32_bf16 v[86:89], v[146:149], v[224:227], 0
	v_mfma_f32_16x16x32_bf16 v[82:85], v[180:183], v[224:227], 0
	v_mfma_f32_16x16x32_bf16 v[70:73], v[146:149], v[232:235], 0
	v_mfma_f32_16x16x32_bf16 v[66:69], v[180:183], v[232:235], 0
	v_mfma_f32_16x16x32_bf16 v[118:121], v[150:153], v[192:195], v[118:121]
	v_mfma_f32_16x16x32_bf16 v[114:117], v[184:187], v[192:195], v[114:117]
	v_mfma_f32_16x16x32_bf16 v[102:105], v[150:153], v[220:223], v[102:105]
	v_mfma_f32_16x16x32_bf16 v[98:101], v[184:187], v[220:223], v[98:101]
	v_mfma_f32_16x16x32_bf16 v[86:89], v[150:153], v[228:231], v[86:89]
	v_mfma_f32_16x16x32_bf16 v[82:85], v[184:187], v[228:231], v[82:85]
	v_mfma_f32_16x16x32_bf16 v[70:73], v[150:153], v[236:239], v[70:73]
	v_mfma_f32_16x16x32_bf16 v[66:69], v[184:187], v[236:239], v[66:69]
	s_branch .Lcz_p3_0_j
.Lcz_p3_1:
	s_barrier
	s_setprio 1
	s_waitcnt lgkmcnt(0)
	v_mfma_f32_16x16x32_bf16 v[62:65], v[130:133], v[188:191], 0
	v_mfma_f32_16x16x32_bf16 v[58:61], v[138:141], v[188:191], 0
	v_mfma_f32_16x16x32_bf16 v[46:49], v[130:133], v[216:219], 0
	v_mfma_f32_16x16x32_bf16 v[42:45], v[138:141], v[216:219], 0
	v_mfma_f32_16x16x32_bf16 v[30:33], v[130:133], v[224:227], 0
	v_mfma_f32_16x16x32_bf16 v[26:29], v[138:141], v[224:227], 0
	v_mfma_f32_16x16x32_bf16 v[14:17], v[130:133], v[232:235], 0
	v_mfma_f32_16x16x32_bf16 v[10:13], v[138:141], v[232:235], 0
	v_mfma_f32_16x16x32_bf16 v[62:65], v[134:137], v[192:195], v[62:65]
	v_mfma_f32_16x16x32_bf16 v[58:61], v[142:145], v[192:195], v[58:61]
	v_mfma_f32_16x16x32_bf16 v[46:49], v[134:137], v[220:223], v[46:49]
	v_mfma_f32_16x16x32_bf16 v[42:45], v[142:145], v[220:223], v[42:45]
	v_mfma_f32_16x16x32_bf16 v[30:33], v[134:137], v[228:231], v[30:33]
	v_mfma_f32_16x16x32_bf16 v[26:29], v[142:145], v[228:231], v[26:29]
	v_mfma_f32_16x16x32_bf16 v[14:17], v[134:137], v[236:239], v[14:17]
	v_mfma_f32_16x16x32_bf16 v[10:13], v[142:145], v[236:239], v[10:13]
	s_setprio 0
	s_setprio 1
	v_mfma_f32_16x16x32_bf16 v[54:57], v[146:149], v[188:191], 0
	v_mfma_f32_16x16x32_bf16 v[50:53], v[180:183], v[188:191], 0
	v_mfma_f32_16x16x32_bf16 v[38:41], v[146:149], v[216:219], 0
	v_mfma_f32_16x16x32_bf16 v[34:37], v[180:183], v[216:219], 0
	v_mfma_f32_16x16x32_bf16 v[22:25], v[146:149], v[224:227], 0
	v_mfma_f32_16x16x32_bf16 v[18:21], v[180:183], v[224:227], 0
	v_mfma_f32_16x16x32_bf16 v[6:9], v[146:149], v[232:235], 0
	v_mfma_f32_16x16x32_bf16 v[2:5], v[180:183], v[232:235], 0
	v_mfma_f32_16x16x32_bf16 v[54:57], v[150:153], v[192:195], v[54:57]
	v_mfma_f32_16x16x32_bf16 v[50:53], v[184:187], v[192:195], v[50:53]
	v_mfma_f32_16x16x32_bf16 v[38:41], v[150:153], v[220:223], v[38:41]
	v_mfma_f32_16x16x32_bf16 v[34:37], v[184:187], v[220:223], v[34:37]
	v_mfma_f32_16x16x32_bf16 v[22:25], v[150:153], v[228:231], v[22:25]
	v_mfma_f32_16x16x32_bf16 v[18:21], v[184:187], v[228:231], v[18:21]
	v_mfma_f32_16x16x32_bf16 v[6:9], v[150:153], v[236:239], v[6:9]
	v_mfma_f32_16x16x32_bf16 v[2:5], v[184:187], v[236:239], v[2:5]
	s_branch .Lcz_p3_1_j

; #define PG8_WAIT_V(n) asm volatile("s_waitcnt vmcnt(" #n ")" ::: "memory")
; template <class Epi>
; __device__ __forceinline__ void gemm_phase(LAS unsigned char* lds, const Gemm g, const Sched& S, const Epi& E) {
;     ...
;         const char* nA = has_next ? (const char*)g.A + (size_t)nxt.pm * tstepA + (size_t)nxt.part * g.koff * 2 : cA; const char* nB = has_next ? (const char*)g.Bt + (size_t)nxt.pn * tstepB + (size_t)nxt.part * g.koff * 2 : cB;
;         for (int t = 0; t < nt; t += 2) {
;             const bool last = (t == nt - 2);
;             const char* a1 = cA + (size_t)(t + 1) * kstep;
;             const char* a2 = last ? nA : cA + (size_t)(t + 2) * kstep; const char* b2 = last ? nB : cB + (size_t)(t + 2) * kstep;
;             const char* a3 = a2 + kstep; const char* b3 = b2 + kstep;
;             PG8_LDB(B0, 0, 0); PG8_LDB(B1, 0, 1); PG8_SCHED; PG8_LDA(At, 0, 0); PG8_STAGE(PG8_SA(1, 1), a1 + hstepA, voffA);
;             PG8_WAIT_V(8); PG8_WAIT_L(0); PG8_BAR; PG8_MMA(0, 0, At, B0); PG8_MMA(0, 1, At, B1); PG8_BAR; PG8_SCHED;
;             PG8_LDA(At, 0, 1); PG8_STAGE(PG8_SB(0, 0), b2, voffB); PG8_STAGE(PG8_SB(0, 1), b2 + hstepB, voffB); PG8_STAGE(PG8_SA(0, 0), a2, voffA);
;             PG8_WAIT_V(8); PG8_WAIT_L(0); PG8_BAR; PG8_MMA(1, 0, At, B0); PG8_MMA(1, 1, At, B1); PG8_BAR; PG8_SCHED;
;             PG8_LDB(B0, 1, 0); PG8_LDB(B1, 1, 1); PG8_SCHED; PG8_LDA(At, 1, 0); PG8_STAGE(PG8_SA(0, 1), a2 + hstepA, voffA);
;             PG8_WAIT_V(8); PG8_WAIT_L(0); PG8_BAR; PG8_MMA(0, 0, At, B0); PG8_MMA(0, 1, At, B1); PG8_BAR; PG8_SCHED;
;             PG8_LDA(At, 1, 1); PG8_STAGE(PG8_SB(1, 0), b3, voffB); PG8_STAGE(PG8_SB(1, 1), b3 + hstepB, voffB); PG8_STAGE(PG8_SA(1, 0), a3, voffA);
;             PG8_WAIT_V(8); PG8_WAIT_L(0); PG8_BAR; PG8_MMA(1, 0, At, B0); PG8_MMA(1, 1, At, B1); PG8_BAR; PG8_SCHED;
;         }
;         if (wr == 0) PG8_BAR;
;         if constexpr (!Epi::AFTER_DRAIN) E(acc, cur, wr, wc, fr, fq);
;         if (!has_next) break;
;         if (!(Epi::KEEP_PART0 && cur.part == 0))
; #pragma unroll
;         for (int a = 0; a < 2; ++a)
; #pragma unroll
;             for (int b = 0; b < 2; ++b)
; #pragma unroll
;                 for (int m = 0; m < 4; ++m)
; #pragma unroll
;                     for (int n = 0; n < 2; ++n) acc[a][b][m][n] = (f32x4){0.f, 0.f, 0.f, 0.f};
;         cur = nxt; cA = nA; cB = nB; ++ui;
.LBB0_1717:
	s_ashr_i32 s15, s14, 31
	s_lshl_b64 s[16:17], s[14:15], 19
	s_add_u32 s16, s40, s16
	s_addc_u32 s17, s41, s17
	s_and_b64 s[18:19], s[0:1], exec
	s_cselect_b32 s15, s17, s23
	s_cselect_b32 s45, s16, s22
	s_ashr_i32 s11, s10, 31
	s_lshl_b64 s[18:19], s[10:11], 19
	v_readlane_b32 s26, v252, 9
	v_readlane_b32 s27, v252, 10
	s_add_u32 s18, s26, s18
	s_addc_u32 s19, s27, s19
	s_and_b64 s[26:27], s[0:1], exec
	s_cselect_b32 s11, s19, s25
	s_cselect_b32 s46, s18, s24
	s_add_u32 s22, s22, 0x40080
	s_addc_u32 s23, s23, 0
	s_add_u32 s47, s24, 0x100
	s_addc_u32 s52, s25, 0
	s_mov_b32 s53, -2

; #define PG8_STAGE(bufoff, gbase, voff) do { _Pragma("unroll") for (int _i = 0; _i < 2; ++_i) \
;         __builtin_amdgcn_global_load_lds((const unsigned*)((const char*)(gbase) + (voff)[_i]), (LAS unsigned*)(lds + (bufoff) + ldsw + _i * 8192), 16, 0, 0); } while (0)
; #define PG8_LDA(dst, b, h) do { _Pragma("unroll") for (int m = 0; m < 4; ++m) _Pragma("unroll") for (int k = 0; k < 2; ++k) dst[m][k] = *(const LAS bf16x8*)(lds + PG8_SA(b, h) + aoff + m * 2048 + k * 1024); } while (0)
; #define PG8_LDB(dst, b, h) do { _Pragma("unroll") for (int n = 0; n < 2; ++n) _Pragma("unroll") for (int k = 0; k < 2; ++k) dst[n][k] = *(const LAS bf16x8*)(lds + PG8_SB(b, h) + boff + n * 2048 + k * 1024); } while (0)
; #define PG8_MMA(ai, bj, At, Bt) do { __builtin_amdgcn_s_setprio(1); _Pragma("unroll") for (int m = 0; m < 4; ++m) _Pragma("unroll") for (int n = 0; n < 2; ++n) _Pragma("unroll") for (int k = 0; k < 2; ++k) \
;         acc[ai][bj][m][n] = __builtin_amdgcn_mfma_f32_16x16x32_bf16(Bt[n][k], At[m][k], acc[ai][bj][m][n], 0, 0, 0); __builtin_amdgcn_s_setprio(0); } while (0)
; #define PG8_WAIT_V(n) asm volatile("s_waitcnt vmcnt(" #n ")" ::: "memory")
; #define PG8_WAIT_L(n) asm volatile("s_waitcnt lgkmcnt(" #n ")" ::: "memory")
; #define PG8_BAR __builtin_amdgcn_s_barrier()
; #define PG8_SCHED __builtin_amdgcn_sched_barrier(0)
; template <class Epi>
; __device__ __forceinline__ void gemm_phase(LAS unsigned char* lds, const Gemm g, const Sched& S, const Epi& E) {
;     ...
;             PG8_LDB(B0, 0, 0); PG8_LDB(B1, 0, 1); PG8_SCHED; PG8_LDA(At, 0, 0); PG8_STAGE(PG8_SA(1, 1), a1 + hstepA, voffA);
;             PG8_WAIT_V(8); PG8_WAIT_L(0); PG8_BAR; PG8_MMA(0, 0, At, B0); PG8_MMA(0, 1, At, B1); PG8_BAR; PG8_SCHED;
;             PG8_LDA(At, 0, 1); PG8_STAGE(PG8_SB(0, 0), b2, voffB); PG8_STAGE(PG8_SB(0, 1), b2 + hstepB, voffB); PG8_STAGE(PG8_SA(0, 0), a2, voffA);
.Lrx_p9_0_j:
	s_waitcnt lgkmcnt(0)
	s_cmp_eq_u32 s53, -2
	s_cbranch_scc1 .Lcz_p9_0
	s_barrier
	s_setprio 1
	s_waitcnt lgkmcnt(0)
	v_mfma_f32_16x16x32_bf16 v[126:129], v[156:159], v[188:191], v[126:129]
	v_mfma_f32_16x16x32_bf16 v[122:125], v[164:167], v[188:191], v[122:125]
	v_mfma_f32_16x16x32_bf16 v[110:113], v[156:159], v[200:203], v[110:113]
	v_mfma_f32_16x16x32_bf16 v[106:109], v[164:167], v[200:203], v[106:109]
	v_mfma_f32_16x16x32_bf16 v[94:97], v[156:159], v[208:211], v[94:97]
	v_mfma_f32_16x16x32_bf16 v[90:93], v[164:167], v[208:211], v[90:93]
	v_mfma_f32_16x16x32_bf16 v[78:81], v[156:159], v[216:219], v[78:81]
	v_mfma_f32_16x16x32_bf16 v[74:77], v[164:167], v[216:219], v[74:77]
	v_mfma_f32_16x16x32_bf16 v[126:129], v[160:163], v[192:195], v[126:129]
	v_mfma_f32_16x16x32_bf16 v[122:125], v[168:171], v[192:195], v[122:125]
	v_mfma_f32_16x16x32_bf16 v[110:113], v[160:163], v[204:207], v[110:113]
	v_mfma_f32_16x16x32_bf16 v[106:109], v[168:171], v[204:207], v[106:109]
	v_mfma_f32_16x16x32_bf16 v[94:97], v[160:163], v[212:215], v[94:97]
	v_mfma_f32_16x16x32_bf16 v[90:93], v[168:171], v[212:215], v[90:93]
	v_mfma_f32_16x16x32_bf16 v[78:81], v[160:163], v[220:223], v[78:81]
	v_mfma_f32_16x16x32_bf16 v[74:77], v[168:171], v[220:223], v[74:77]
	s_setprio 0
	s_setprio 1
	v_mfma_f32_16x16x32_bf16 v[118:121], v[172:175], v[188:191], v[118:121]
	v_mfma_f32_16x16x32_bf16 v[114:117], v[180:183], v[188:191], v[114:117]
	v_mfma_f32_16x16x32_bf16 v[102:105], v[172:175], v[200:203], v[102:105]
	v_mfma_f32_16x16x32_bf16 v[98:101], v[180:183], v[200:203], v[98:101]
	v_mfma_f32_16x16x32_bf16 v[86:89], v[172:175], v[208:211], v[86:89]
	v_mfma_f32_16x16x32_bf16 v[82:85], v[180:183], v[208:211], v[82:85]
	v_mfma_f32_16x16x32_bf16 v[70:73], v[172:175], v[216:219], v[70:73]
	v_mfma_f32_16x16x32_bf16 v[66:69], v[180:183], v[216:219], v[66:69]
	v_mfma_f32_16x16x32_bf16 v[118:121], v[176:179], v[192:195], v[118:121]
	v_mfma_f32_16x16x32_bf16 v[114:117], v[184:187], v[192:195], v[114:117]
	v_mfma_f32_16x16x32_bf16 v[102:105], v[176:179], v[204:207], v[102:105]
	v_mfma_f32_16x16x32_bf16 v[98:101], v[184:187], v[204:207], v[98:101]
	v_mfma_f32_16x16x32_bf16 v[86:89], v[176:179], v[212:215], v[86:89]
	v_mfma_f32_16x16x32_bf16 v[82:85], v[184:187], v[212:215], v[82:85]
	v_mfma_f32_16x16x32_bf16 v[70:73], v[176:179], v[220:223], v[70:73]
	v_mfma_f32_16x16x32_bf16 v[66:69], v[184:187], v[220:223], v[66:69]
.Lcz_p9_0_j:
	s_setprio 0
	s_barrier
	s_add_i32 s54, s36, s29
	v_lshl_add_u64 v[196:197], s[24:25], 0, v[132:133]
	s_mov_b32 m0, s54
	ds_read_b128 v[188:191], v155 offset:16384
	ds_read_b128 v[192:195], v155 offset:17408
	ds_read_b128 v[200:203], v155 offset:18432
	ds_read_b128 v[204:207], v155 offset:19456
	ds_read_b128 v[208:211], v155 offset:20480
	ds_read_b128 v[212:215], v155 offset:21504
	ds_read_b128 v[216:219], v155 offset:22528
	ds_read_b128 v[220:223], v155 offset:23552
	global_load_lds_dwordx4 v[196:197], off
	s_add_i32 m0, s54, 0x2000
	s_add_u32 s54, s24, 0x40000
	v_lshl_add_u64 v[224:225], s[24:25], 0, v[136:137]
	s_addc_u32 s55, s25, 0
	s_add_i32 s56, s37, s29
	global_load_lds_dwordx4 v[224:225], off
	v_lshl_add_u64 v[226:227], s[54:55], 0, v[132:133]
	s_mov_b32 m0, s56
	v_lshl_add_u64 v[228:229], s[26:27], 0, v[134:135]
	global_load_lds_dwordx4 v[226:227], off
	v_lshl_add_u64 v[226:227], s[54:55], 0, v[136:137]
	s_add_i32 m0, s56, 0x2000
	s_nop 0
	global_load_lds_dwordx4 v[226:227], off
	v_lshl_add_u64 v[226:227], s[26:27], 0, v[130:131]
	s_mov_b32 m0, s21
	s_nop 0
	global_load_lds_dwordx4 v[226:227], off
	s_mov_b32 m0, s30
	s_nop 0
	global_load_lds_dwordx4 v[228:229], off
	s_cmp_eq_u32 s98, 0
	s_cbranch_scc1 .Lrx_p9_1_n
	s_sub_u32 s98, s98, 1
	s_waitcnt vmcnt(16)
	s_branch .Lrx_p9_1_j

; #define PG8_STAGE(bufoff, gbase, voff) do { _Pragma("unroll") for (int _i = 0; _i < 2; ++_i) \
;         __builtin_amdgcn_global_load_lds((const unsigned*)((const char*)(gbase) + (voff)[_i]), (LAS unsigned*)(lds + (bufoff) + ldsw + _i * 8192), 16, 0, 0); } while (0)
; #define PG8_LDA(dst, b, h) do { _Pragma("unroll") for (int m = 0; m < 4; ++m) _Pragma("unroll") for (int k = 0; k < 2; ++k) dst[m][k] = *(const LAS bf16x8*)(lds + PG8_SA(b, h) + aoff + m * 2048 + k * 1024); } while (0)
; #define PG8_LDB(dst, b, h) do { _Pragma("unroll") for (int n = 0; n < 2; ++n) _Pragma("unroll") for (int k = 0; k < 2; ++k) dst[n][k] = *(const LAS bf16x8*)(lds + PG8_SB(b, h) + boff + n * 2048 + k * 1024); } while (0)
; #define PG8_MMA(ai, bj, At, Bt) do { __builtin_amdgcn_s_setprio(1); _Pragma("unroll") for (int m = 0; m < 4; ++m) _Pragma("unroll") for (int n = 0; n < 2; ++n) _Pragma("unroll") for (int k = 0; k < 2; ++k) \
;         acc[ai][bj][m][n] = __builtin_amdgcn_mfma_f32_16x16x32_bf16(Bt[n][k], At[m][k], acc[ai][bj][m][n], 0, 0, 0); __builtin_amdgcn_s_setprio(0); } while (0)
; #define PG8_WAIT_V(n) asm volatile("s_waitcnt vmcnt(" #n ")" ::: "memory")
; #define PG8_WAIT_L(n) asm volatile("s_waitcnt lgkmcnt(" #n ")" ::: "memory")
; #define PG8_BAR __builtin_amdgcn_s_barrier()
; #define PG8_SCHED __builtin_amdgcn_sched_barrier(0)
; template <class Epi>
; __device__ __forceinline__ void gemm_phase(LAS unsigned char* lds, const Gemm g, const Sched& S, const Epi& E) {
;     ...
;             PG8_WAIT_V(8); PG8_WAIT_L(0); PG8_BAR; PG8_MMA(1, 0, At, B0); PG8_MMA(1, 1, At, B1); PG8_BAR; PG8_SCHED;
;             PG8_LDB(B0, 1, 0); PG8_LDB(B1, 1, 1); PG8_SCHED; PG8_LDA(At, 1, 0); PG8_STAGE(PG8_SA(0, 1), a2 + hstepA, voffA);
;             PG8_WAIT_V(8); PG8_WAIT_L(0); PG8_BAR; PG8_MMA(0, 0, At, B0); PG8_MMA(0, 1, At, B1); PG8_BAR; PG8_SCHED;
.Lrx_p9_1_j:
	s_waitcnt lgkmcnt(0)
	s_cmp_eq_u32 s53, -2
	s_cbranch_scc1 .Lcz_p9_1
	s_barrier
	s_setprio 1
	s_waitcnt lgkmcnt(0)
	v_mfma_f32_16x16x32_bf16 v[62:65], v[156:159], v[188:191], v[62:65]
	v_mfma_f32_16x16x32_bf16 v[58:61], v[164:167], v[188:191], v[58:61]
	v_mfma_f32_16x16x32_bf16 v[46:49], v[156:159], v[200:203], v[46:49]
	v_mfma_f32_16x16x32_bf16 v[42:45], v[164:167], v[200:203], v[42:45]
	v_mfma_f32_16x16x32_bf16 v[30:33], v[156:159], v[208:211], v[30:33]
	v_mfma_f32_16x16x32_bf16 v[26:29], v[164:167], v[208:211], v[26:29]
	v_mfma_f32_16x16x32_bf16 v[14:17], v[156:159], v[216:219], v[14:17]
	v_mfma_f32_16x16x32_bf16 v[10:13], v[164:167], v[216:219], v[10:13]
	v_mfma_f32_16x16x32_bf16 v[62:65], v[160:163], v[192:195], v[62:65]
	v_mfma_f32_16x16x32_bf16 v[58:61], v[168:171], v[192:195], v[58:61]
	v_mfma_f32_16x16x32_bf16 v[46:49], v[160:163], v[204:207], v[46:49]
	v_mfma_f32_16x16x32_bf16 v[42:45], v[168:171], v[204:207], v[42:45]
	v_mfma_f32_16x16x32_bf16 v[30:33], v[160:163], v[212:215], v[30:33]
	v_mfma_f32_16x16x32_bf16 v[26:29], v[168:171], v[212:215], v[26:29]
	v_mfma_f32_16x16x32_bf16 v[14:17], v[160:163], v[220:223], v[14:17]
	v_mfma_f32_16x16x32_bf16 v[10:13], v[168:171], v[220:223], v[10:13]
	s_setprio 0
	s_setprio 1
	v_mfma_f32_16x16x32_bf16 v[54:57], v[172:175], v[188:191], v[54:57]
	v_mfma_f32_16x16x32_bf16 v[50:53], v[180:183], v[188:191], v[50:53]
	v_mfma_f32_16x16x32_bf16 v[38:41], v[172:175], v[200:203], v[38:41]
	v_mfma_f32_16x16x32_bf16 v[34:37], v[180:183], v[200:203], v[34:37]
	v_mfma_f32_16x16x32_bf16 v[22:25], v[172:175], v[208:211], v[22:25]
	v_mfma_f32_16x16x32_bf16 v[18:21], v[180:183], v[208:211], v[18:21]
	v_mfma_f32_16x16x32_bf16 v[6:9], v[172:175], v[216:219], v[6:9]
	v_mfma_f32_16x16x32_bf16 v[2:5], v[180:183], v[216:219], v[2:5]
	v_mfma_f32_16x16x32_bf16 v[54:57], v[176:179], v[192:195], v[54:57]
	v_mfma_f32_16x16x32_bf16 v[50:53], v[184:187], v[192:195], v[50:53]
	v_mfma_f32_16x16x32_bf16 v[38:41], v[176:179], v[204:207], v[38:41]
	v_mfma_f32_16x16x32_bf16 v[34:37], v[184:187], v[204:207], v[34:37]
	v_mfma_f32_16x16x32_bf16 v[22:25], v[176:179], v[212:215], v[22:25]
	v_mfma_f32_16x16x32_bf16 v[18:21], v[184:187], v[212:215], v[18:21]
	v_mfma_f32_16x16x32_bf16 v[6:9], v[176:179], v[220:223], v[6:9]
	v_mfma_f32_16x16x32_bf16 v[2:5], v[184:187], v[220:223], v[2:5]
.Lcz_p9_1_j:
	s_setprio 0
	s_barrier
	s_add_i32 s54, 0, 0x18000
	s_add_i32 s55, 0, 0x1c000
	v_add_u32_e32 v168, s54, v147
	v_add_u32_e32 v184, s55, v147
	ds_read_b128 v[156:159], v168
	ds_read_b128 v[160:163], v168 offset:1024
	ds_read_b128 v[164:167], v168 offset:2048
	ds_read_b128 v[168:171], v168 offset:3072
	ds_read_b128 v[172:175], v184
	ds_read_b128 v[176:179], v184 offset:1024
	ds_read_b128 v[180:183], v184 offset:2048
	ds_read_b128 v[184:187], v184 offset:3072
	s_add_u32 s26, s26, 0x40000
	s_addc_u32 s27, s27, 0
	s_mov_b32 m0, s31
	v_lshl_add_u64 v[230:231], s[26:27], 0, v[130:131]
	ds_read_b128 v[188:191], v155 offset:32768
	ds_read_b128 v[192:195], v155 offset:33792
	ds_read_b128 v[200:203], v155 offset:34816
	ds_read_b128 v[204:207], v155 offset:35840
	ds_read_b128 v[208:211], v155 offset:36864
	ds_read_b128 v[212:215], v155 offset:37888
	ds_read_b128 v[216:219], v155 offset:38912
	ds_read_b128 v[220:223], v155 offset:39936
	global_load_lds_dwordx4 v[230:231], off
	v_lshl_add_u64 v[230:231], s[26:27], 0, v[134:135]
	s_mov_b32 m0, s33
	s_nop 0
	global_load_lds_dwordx4 v[230:231], off
	s_waitcnt vmcnt(8)
	s_waitcnt lgkmcnt(0)
	s_barrier
	s_setprio 1
	s_waitcnt lgkmcnt(0)
	v_mfma_f32_16x16x32_bf16 v[126:129], v[156:159], v[188:191], v[126:129]
	v_mfma_f32_16x16x32_bf16 v[122:125], v[164:167], v[188:191], v[122:125]
	v_mfma_f32_16x16x32_bf16 v[110:113], v[156:159], v[200:203], v[110:113]
	v_mfma_f32_16x16x32_bf16 v[106:109], v[164:167], v[200:203], v[106:109]
	v_mfma_f32_16x16x32_bf16 v[94:97], v[156:159], v[208:211], v[94:97]
	v_mfma_f32_16x16x32_bf16 v[90:93], v[164:167], v[208:211], v[90:93]
	v_mfma_f32_16x16x32_bf16 v[78:81], v[156:159], v[216:219], v[78:81]
	v_mfma_f32_16x16x32_bf16 v[74:77], v[164:167], v[216:219], v[74:77]
	v_mfma_f32_16x16x32_bf16 v[126:129], v[160:163], v[192:195], v[126:129]
	v_mfma_f32_16x16x32_bf16 v[122:125], v[168:171], v[192:195], v[122:125]
	v_mfma_f32_16x16x32_bf16 v[110:113], v[160:163], v[204:207], v[110:113]
	v_mfma_f32_16x16x32_bf16 v[106:109], v[168:171], v[204:207], v[106:109]
	v_mfma_f32_16x16x32_bf16 v[94:97], v[160:163], v[212:215], v[94:97]
	v_mfma_f32_16x16x32_bf16 v[90:93], v[168:171], v[212:215], v[90:93]
	v_mfma_f32_16x16x32_bf16 v[78:81], v[160:163], v[220:223], v[78:81]
	v_mfma_f32_16x16x32_bf16 v[74:77], v[168:171], v[220:223], v[74:77]
	s_setprio 0
	s_setprio 1
	v_mfma_f32_16x16x32_bf16 v[118:121], v[172:175], v[188:191], v[118:121]
	v_mfma_f32_16x16x32_bf16 v[114:117], v[180:183], v[188:191], v[114:117]
	v_mfma_f32_16x16x32_bf16 v[102:105], v[172:175], v[200:203], v[102:105]
	v_mfma_f32_16x16x32_bf16 v[98:101], v[180:183], v[200:203], v[98:101]
	v_mfma_f32_16x16x32_bf16 v[86:89], v[172:175], v[208:211], v[86:89]
	v_mfma_f32_16x16x32_bf16 v[82:85], v[180:183], v[208:211], v[82:85]
	v_mfma_f32_16x16x32_bf16 v[70:73], v[172:175], v[216:219], v[70:73]
	v_mfma_f32_16x16x32_bf16 v[66:69], v[180:183], v[216:219], v[66:69]
	v_mfma_f32_16x16x32_bf16 v[118:121], v[176:179], v[192:195], v[118:121]
	v_mfma_f32_16x16x32_bf16 v[114:117], v[184:187], v[192:195], v[114:117]
	v_mfma_f32_16x16x32_bf16 v[102:105], v[176:179], v[204:207], v[102:105]
	v_mfma_f32_16x16x32_bf16 v[98:101], v[184:187], v[204:207], v[98:101]
	v_mfma_f32_16x16x32_bf16 v[86:89], v[176:179], v[212:215], v[86:89]
	v_mfma_f32_16x16x32_bf16 v[82:85], v[184:187], v[212:215], v[82:85]
	v_mfma_f32_16x16x32_bf16 v[70:73], v[176:179], v[220:223], v[70:73]
	v_mfma_f32_16x16x32_bf16 v[66:69], v[184:187], v[220:223], v[66:69]
	s_setprio 0
	s_barrier
; #define PG8_STAGE(bufoff, gbase, voff) do { _Pragma("unroll") for (int _i = 0; _i < 2; ++_i) \
;         __builtin_amdgcn_global_load_lds((const unsigned*)((const char*)(gbase) + (voff)[_i]), (LAS unsigned*)(lds + (bufoff) + ldsw + _i * 8192), 16, 0, 0); } while (0)
; #define PG8_LDA(dst, b, h) do { _Pragma("unroll") for (int m = 0; m < 4; ++m) _Pragma("unroll") for (int k = 0; k < 2; ++k) dst[m][k] = *(const LAS bf16x8*)(lds + PG8_SA(b, h) + aoff + m * 2048 + k * 1024); } while (0)
; #define PG8_MMA(ai, bj, At, Bt) do { __builtin_amdgcn_s_setprio(1); _Pragma("unroll") for (int m = 0; m < 4; ++m) _Pragma("unroll") for (int n = 0; n < 2; ++n) _Pragma("unroll") for (int k = 0; k < 2; ++k) \
;         acc[ai][bj][m][n] = __builtin_amdgcn_mfma_f32_16x16x32_bf16(Bt[n][k], At[m][k], acc[ai][bj][m][n], 0, 0, 0); __builtin_amdgcn_s_setprio(0); } while (0)
; #define PG8_WAIT_V(n) asm volatile("s_waitcnt vmcnt(" #n ")" ::: "memory")
; #define PG8_WAIT_L(n) asm volatile("s_waitcnt lgkmcnt(" #n ")" ::: "memory")
; #define PG8_BAR __builtin_amdgcn_s_barrier()
; #define PG8_SCHED __builtin_amdgcn_sched_barrier(0)
; template <class Epi>
; __device__ __forceinline__ void gemm_phase(LAS unsigned char* lds, const Gemm g, const Sched& S, const Epi& E) {
;     ...
;             PG8_LDA(At, 1, 1); PG8_STAGE(PG8_SB(1, 0), b3, voffB); PG8_STAGE(PG8_SB(1, 1), b3 + hstepB, voffB); PG8_STAGE(PG8_SA(1, 0), a3, voffA);
;             PG8_WAIT_V(8); PG8_WAIT_L(0); PG8_BAR; PG8_MMA(1, 0, At, B0); PG8_MMA(1, 1, At, B1); PG8_BAR; PG8_SCHED;
;         }
;         if (wr == 0) PG8_BAR;
;         if constexpr (!Epi::AFTER_DRAIN) E(acc, cur, wr, wc, fr, fq);
;         if (!has_next) break;
	s_add_i32 s26, s54, s29
	v_lshl_add_u64 v[196:197], v[196:197], 0, s[6:7]
	s_mov_b32 m0, s26
	ds_read_b128 v[188:191], v155 offset:49152
	ds_read_b128 v[192:195], v155 offset:50176
	ds_read_b128 v[200:203], v155 offset:51200
	ds_read_b128 v[204:207], v155 offset:52224
	ds_read_b128 v[208:211], v155 offset:53248
	ds_read_b128 v[212:215], v155 offset:54272
	ds_read_b128 v[216:219], v155 offset:55296
	ds_read_b128 v[220:223], v155 offset:56320
	global_load_lds_dwordx4 v[196:197], off
	s_add_i32 m0, s26, 0x2000
	s_add_u32 s24, s24, 0x40080
	v_lshl_add_u64 v[196:197], v[224:225], 0, s[6:7]
	s_addc_u32 s25, s25, 0
	s_add_i32 s26, s55, s29
	global_load_lds_dwordx4 v[196:197], off
	v_lshl_add_u64 v[196:197], s[24:25], 0, v[132:133]
	s_mov_b32 m0, s26
	s_nop 0
	global_load_lds_dwordx4 v[196:197], off
	v_lshl_add_u64 v[196:197], s[24:25], 0, v[136:137]
	s_add_i32 m0, s26, 0x2000
	s_nop 0
	global_load_lds_dwordx4 v[196:197], off
	v_lshl_add_u64 v[196:197], v[226:227], 0, s[6:7]
	s_mov_b32 m0, s34
	s_nop 0
	global_load_lds_dwordx4 v[196:197], off
	v_lshl_add_u64 v[196:197], v[228:229], 0, s[6:7]
	s_mov_b32 m0, s35
	s_nop 0
	global_load_lds_dwordx4 v[196:197], off
	s_waitcnt vmcnt(8)
	s_waitcnt lgkmcnt(0)
	s_barrier
	s_setprio 1
	s_waitcnt lgkmcnt(0)
	v_mfma_f32_16x16x32_bf16 v[62:65], v[156:159], v[188:191], v[62:65]
	v_mfma_f32_16x16x32_bf16 v[58:61], v[164:167], v[188:191], v[58:61]
	v_mfma_f32_16x16x32_bf16 v[46:49], v[156:159], v[200:203], v[46:49]
	v_mfma_f32_16x16x32_bf16 v[42:45], v[164:167], v[200:203], v[42:45]
	v_mfma_f32_16x16x32_bf16 v[30:33], v[156:159], v[208:211], v[30:33]
	v_mfma_f32_16x16x32_bf16 v[26:29], v[164:167], v[208:211], v[26:29]
	v_mfma_f32_16x16x32_bf16 v[14:17], v[156:159], v[216:219], v[14:17]
	v_mfma_f32_16x16x32_bf16 v[10:13], v[164:167], v[216:219], v[10:13]
	v_mfma_f32_16x16x32_bf16 v[62:65], v[160:163], v[192:195], v[62:65]
	v_mfma_f32_16x16x32_bf16 v[58:61], v[168:171], v[192:195], v[58:61]
	v_mfma_f32_16x16x32_bf16 v[46:49], v[160:163], v[204:207], v[46:49]
	v_mfma_f32_16x16x32_bf16 v[42:45], v[168:171], v[204:207], v[42:45]
	v_mfma_f32_16x16x32_bf16 v[30:33], v[160:163], v[212:215], v[30:33]
	v_mfma_f32_16x16x32_bf16 v[26:29], v[168:171], v[212:215], v[26:29]
	v_mfma_f32_16x16x32_bf16 v[14:17], v[160:163], v[220:223], v[14:17]
	v_mfma_f32_16x16x32_bf16 v[10:13], v[168:171], v[220:223], v[10:13]
	s_setprio 0
	s_setprio 1
	v_mfma_f32_16x16x32_bf16 v[54:57], v[172:175], v[188:191], v[54:57]
	v_mfma_f32_16x16x32_bf16 v[50:53], v[180:183], v[188:191], v[50:53]
	v_mfma_f32_16x16x32_bf16 v[38:41], v[172:175], v[200:203], v[38:41]
	v_mfma_f32_16x16x32_bf16 v[34:37], v[180:183], v[200:203], v[34:37]
	v_mfma_f32_16x16x32_bf16 v[22:25], v[172:175], v[208:211], v[22:25]
	v_mfma_f32_16x16x32_bf16 v[18:21], v[180:183], v[208:211], v[18:21]
	v_mfma_f32_16x16x32_bf16 v[6:9], v[172:175], v[216:219], v[6:9]
	v_mfma_f32_16x16x32_bf16 v[2:5], v[180:183], v[216:219], v[2:5]
	v_mfma_f32_16x16x32_bf16 v[54:57], v[176:179], v[192:195], v[54:57]
	v_mfma_f32_16x16x32_bf16 v[50:53], v[184:187], v[192:195], v[50:53]
	v_mfma_f32_16x16x32_bf16 v[38:41], v[176:179], v[204:207], v[38:41]
	v_mfma_f32_16x16x32_bf16 v[34:37], v[184:187], v[204:207], v[34:37]
	v_mfma_f32_16x16x32_bf16 v[22:25], v[176:179], v[212:215], v[22:25]
	v_mfma_f32_16x16x32_bf16 v[18:21], v[184:187], v[212:215], v[18:21]
	v_mfma_f32_16x16x32_bf16 v[6:9], v[176:179], v[220:223], v[6:9]
	v_mfma_f32_16x16x32_bf16 v[2:5], v[184:187], v[220:223], v[2:5]
	s_setprio 0
	s_barrier
	s_add_i32 s53, s53, 2
	s_add_u32 s22, s22, 0x100
	s_addc_u32 s23, s23, 0
	s_add_u32 s47, s47, 0x100
	s_addc_u32 s52, s52, 0
	s_cmp_gt_u32 s53, 13
	s_cbranch_scc0 .LBB0_1718
	s_and_b64 vcc, exec, s[8:9]
	s_cbranch_vccz .LBB0_1721
	s_barrier
